# GEMM K-loops: per-iteration next-tile pointer select SALU block moved below SP1's ds_read/DMA issue (reads start earlier)
# speedup vs baseline: 1.0095x; 1.0011x over previous
; #define PG8_STAGE(bufoff, gbase, voff) do { _Pragma("unroll") for (int _i = 0; _i < 2; ++_i) \
;         __builtin_amdgcn_global_load_lds((const unsigned*)((const char*)(gbase) + (voff)[_i]), (PG8_LAS unsigned*)(lds + (bufoff) + ldsw + _i * 8192), 16, 0, 0); } while (0)
; #define PG8_LDA(dst, b, h) do { _Pragma("unroll") for (int m = 0; m < 4; ++m) _Pragma("unroll") for (int k = 0; k < 2; ++k) dst[m][k] = *(const PG8_LAS bf16x8*)(lds + PG8_SA(b, h) + aoff + m * 2048 + k * 1024); } while (0)
; #define PG8_LDB(dst, b, h) do { _Pragma("unroll") for (int n = 0; n < 2; ++n) _Pragma("unroll") for (int k = 0; k < 2; ++k) dst[n][k] = *(const PG8_LAS bf16x8*)(lds + PG8_SB(b, h) + boff + n * 2048 + k * 1024); } while (0)
; #define PG8_MMA(ai, bj, At, Bt) do { __builtin_amdgcn_s_setprio(1); _Pragma("unroll") for (int m = 0; m < 4; ++m) _Pragma("unroll") for (int n = 0; n < 2; ++n) _Pragma("unroll") for (int k = 0; k < 2; ++k) \
;         acc[ai][bj][m][n] = __builtin_amdgcn_mfma_f32_16x16x32_bf16(Bt[n][k], At[m][k], acc[ai][bj][m][n], 0, 0, 0); __builtin_amdgcn_s_setprio(0); } while (0)
; #define PG8_WAIT_V(n) asm volatile("s_waitcnt vmcnt(" #n ")" ::: "memory")
; #define PG8_WAIT_L(n) asm volatile("s_waitcnt lgkmcnt(" #n ")" ::: "memory")
; template <class Epi, class Sched, bool ALIGN_EPI = false, bool SP2 = false>
; __device__ __forceinline__ void gemm_phase(PG8_LAS unsigned char* lds, const Gemm g, const Sched& S, const Epi& E) {
;     ...
;             const bool last = (t == nt - 2);
;             const char* a1 = cA + (size_t)(t + 1) * kstep;
;             const char* a2 = last ? nA : cA + (size_t)(t + 2) * kstep; const char* b2 = last ? nB : cB + (size_t)(t + 2) * kstep;
;             const char* a3 = a2 + kstep; const char* b3 = b2 + kstep;
;             if (last && has_next) S.a_ready(nxt);
;             if constexpr (SP2) {
;             PG8_LDB(B0, 0, 0); PG8_LDB(B1, 0, 1); PG8_SCHED; PG8_LDA(At, 0, 0); PG8_STAGE(PG8_SA(1, 1), a1 + hstep, voffA);
;             PG8_WAIT_V(8); PG8_WAIT_L(0); PG8_BAR; PG8_MMA(0, 0, At, B0); PG8_MMA(0, 1, At, B1); PG8_BAR; PG8_SCHED;
;             PG8_LDA(At, 0, 1); PG8_STAGE(PG8_SB(0, 0), b2, voffB); PG8_STAGE(PG8_SB(0, 1), b2 + hstep, voffB); PG8_STAGE(PG8_SA(0, 0), a2, voffA);
;             PG8_WAIT_V(8); PG8_WAIT_L(0); PG8_BAR; PG8_MMA(1, 0, At, B0); PG8_MMA(1, 1, At, B1); PG8_BAR; PG8_SCHED;
.LBB0_25:
	s_add_i32 s88, 0, 0x10000
	s_add_i32 s90, 0, 0x14000
	v_add_u32_e32 v154, s88, v139
	v_add_u32_e32 v158, s90, v139
	ds_read_b128 v[142:145], v154
	ds_read_b128 v[146:149], v154 offset:1024
	ds_read_b128 v[150:153], v154 offset:2048
	ds_read_b128 v[154:157], v154 offset:3072
	ds_read_b128 v[164:167], v158
	ds_read_b128 v[168:171], v158 offset:1024
	ds_read_b128 v[172:175], v158 offset:2048
	ds_read_b128 v[176:179], v158 offset:3072
	s_add_i32 m0, s29, 0xc000
	ds_read_b128 v[180:183], v141
	ds_read_b128 v[184:187], v141 offset:1024
	ds_read_b128 v[188:191], v141 offset:2048
	ds_read_b128 v[192:195], v141 offset:3072
	ds_read_b128 v[196:199], v141 offset:4096
	ds_read_b128 v[222:225], v141 offset:5120
	ds_read_b128 v[226:229], v141 offset:6144
	ds_read_b128 v[230:233], v141 offset:7168
	global_load_lds_dwordx4 v134, s[80:81]
	s_add_i32 m0, s29, 0xe000
	s_nop 0
	global_load_lds_dwordx4 v136, s[80:81]
	s_add_u32 s4, s80, 0xfff80080
	s_addc_u32 s5, s81, -1
	s_cmp_eq_u32 s87, 28
	s_cselect_b32 s53, s55, s5
	s_cselect_b32 s52, s83, s4
	s_cselect_b32 s5, s73, s86
	s_cselect_b32 s4, s84, s85
	s_waitcnt vmcnt(8)
	s_waitcnt lgkmcnt(0)
	s_barrier
	s_setprio 1
	s_waitcnt lgkmcnt(0)
	v_mfma_f32_16x16x32_bf16 v[124:127], v[142:145], v[180:183], v[124:127]
	v_mfma_f32_16x16x32_bf16 v[120:123], v[150:153], v[180:183], v[120:123]
	v_mfma_f32_16x16x32_bf16 v[116:119], v[142:145], v[188:191], v[116:119]
	v_mfma_f32_16x16x32_bf16 v[112:115], v[150:153], v[188:191], v[112:115]
	v_mfma_f32_16x16x32_bf16 v[100:103], v[142:145], v[196:199], v[100:103]
	v_mfma_f32_16x16x32_bf16 v[96:99], v[150:153], v[196:199], v[96:99]
	v_mfma_f32_16x16x32_bf16 v[84:87], v[142:145], v[226:229], v[84:87]
	v_mfma_f32_16x16x32_bf16 v[80:83], v[150:153], v[226:229], v[80:83]
	v_mfma_f32_16x16x32_bf16 v[124:127], v[146:149], v[184:187], v[124:127]
	v_mfma_f32_16x16x32_bf16 v[120:123], v[154:157], v[184:187], v[120:123]
	v_mfma_f32_16x16x32_bf16 v[116:119], v[146:149], v[192:195], v[116:119]
	v_mfma_f32_16x16x32_bf16 v[112:115], v[154:157], v[192:195], v[112:115]
	v_mfma_f32_16x16x32_bf16 v[100:103], v[146:149], v[222:225], v[100:103]
	v_mfma_f32_16x16x32_bf16 v[96:99], v[154:157], v[222:225], v[96:99]
	v_mfma_f32_16x16x32_bf16 v[84:87], v[146:149], v[230:233], v[84:87]
	v_mfma_f32_16x16x32_bf16 v[80:83], v[154:157], v[230:233], v[80:83]
	s_setprio 0
	s_setprio 1
	v_mfma_f32_16x16x32_bf16 v[108:111], v[164:167], v[180:183], v[108:111]
	v_mfma_f32_16x16x32_bf16 v[104:107], v[172:175], v[180:183], v[104:107]
	v_mfma_f32_16x16x32_bf16 v[92:95], v[164:167], v[188:191], v[92:95]
	v_mfma_f32_16x16x32_bf16 v[88:91], v[172:175], v[188:191], v[88:91]
	v_mfma_f32_16x16x32_bf16 v[76:79], v[164:167], v[196:199], v[76:79]
	v_mfma_f32_16x16x32_bf16 v[72:75], v[172:175], v[196:199], v[72:75]
	v_mfma_f32_16x16x32_bf16 v[68:71], v[164:167], v[226:229], v[68:71]
	v_mfma_f32_16x16x32_bf16 v[64:67], v[172:175], v[226:229], v[64:67]
	v_mfma_f32_16x16x32_bf16 v[108:111], v[168:171], v[184:187], v[108:111]
	v_mfma_f32_16x16x32_bf16 v[104:107], v[176:179], v[184:187], v[104:107]
	v_mfma_f32_16x16x32_bf16 v[92:95], v[168:171], v[192:195], v[92:95]
	v_mfma_f32_16x16x32_bf16 v[88:91], v[176:179], v[192:195], v[88:91]
	v_mfma_f32_16x16x32_bf16 v[76:79], v[168:171], v[222:225], v[76:79]
	v_mfma_f32_16x16x32_bf16 v[72:75], v[176:179], v[222:225], v[72:75]
	v_mfma_f32_16x16x32_bf16 v[68:71], v[168:171], v[230:233], v[68:71]
	v_mfma_f32_16x16x32_bf16 v[64:67], v[176:179], v[230:233], v[64:67]
	s_setprio 0
	s_barrier
	s_add_i32 s88, s88, s28
	s_mov_b32 m0, s88
	ds_read_b128 v[180:183], v141 offset:16384
	ds_read_b128 v[184:187], v141 offset:17408
	ds_read_b128 v[188:191], v141 offset:18432
	ds_read_b128 v[192:195], v141 offset:19456
	ds_read_b128 v[196:199], v141 offset:20480
	ds_read_b128 v[222:225], v141 offset:21504
	ds_read_b128 v[226:229], v141 offset:22528
	ds_read_b128 v[230:233], v141 offset:23552
	global_load_lds_dwordx4 v160, s[4:5]
	s_add_i32 m0, s88, 0x2000
	s_add_u32 s88, s4, 0x80000
	s_addc_u32 s89, s5, 0
	s_add_i32 s90, s90, s28
	global_load_lds_dwordx4 v128, s[4:5]
	s_mov_b32 m0, s90
	s_nop 0
	global_load_lds_dwordx4 v160, s[88:89]
	s_add_i32 m0, s90, 0x2000
	s_nop 0
	global_load_lds_dwordx4 v128, s[88:89]
	s_mov_b32 m0, s29
	s_nop 0
	global_load_lds_dwordx4 v132, s[52:53]
	s_mov_b32 m0, s45
	s_nop 0
	global_load_lds_dwordx4 v130, s[52:53]
	s_add_u32 s98, s52, 0x80
	s_addc_u32 s99, s53, 0
	s_waitcnt vmcnt(8)
	s_waitcnt lgkmcnt(0)
	s_barrier
	s_setprio 1
	s_waitcnt lgkmcnt(0)
	v_mfma_f32_16x16x32_bf16 v[60:63], v[142:145], v[180:183], v[60:63]
	v_mfma_f32_16x16x32_bf16 v[56:59], v[150:153], v[180:183], v[56:59]
	v_mfma_f32_16x16x32_bf16 v[52:55], v[142:145], v[188:191], v[52:55]
	v_mfma_f32_16x16x32_bf16 v[48:51], v[150:153], v[188:191], v[48:51]
	v_mfma_f32_16x16x32_bf16 v[36:39], v[142:145], v[196:199], v[36:39]
	v_mfma_f32_16x16x32_bf16 v[32:35], v[150:153], v[196:199], v[32:35]
	v_mfma_f32_16x16x32_bf16 v[20:23], v[142:145], v[226:229], v[20:23]
	v_mfma_f32_16x16x32_bf16 v[16:19], v[150:153], v[226:229], v[16:19]
	v_mfma_f32_16x16x32_bf16 v[60:63], v[146:149], v[184:187], v[60:63]
	v_mfma_f32_16x16x32_bf16 v[56:59], v[154:157], v[184:187], v[56:59]
	v_mfma_f32_16x16x32_bf16 v[52:55], v[146:149], v[192:195], v[52:55]
	v_mfma_f32_16x16x32_bf16 v[48:51], v[154:157], v[192:195], v[48:51]
	v_mfma_f32_16x16x32_bf16 v[36:39], v[146:149], v[222:225], v[36:39]
	v_mfma_f32_16x16x32_bf16 v[32:35], v[154:157], v[222:225], v[32:35]
	v_mfma_f32_16x16x32_bf16 v[20:23], v[146:149], v[230:233], v[20:23]
	v_mfma_f32_16x16x32_bf16 v[16:19], v[154:157], v[230:233], v[16:19]
	s_setprio 0
	s_setprio 1
	v_mfma_f32_16x16x32_bf16 v[44:47], v[164:167], v[180:183], v[44:47]
	v_mfma_f32_16x16x32_bf16 v[40:43], v[172:175], v[180:183], v[40:43]
	v_mfma_f32_16x16x32_bf16 v[28:31], v[164:167], v[188:191], v[28:31]
	v_mfma_f32_16x16x32_bf16 v[24:27], v[172:175], v[188:191], v[24:27]
	v_mfma_f32_16x16x32_bf16 v[12:15], v[164:167], v[196:199], v[12:15]
	v_mfma_f32_16x16x32_bf16 v[8:11], v[172:175], v[196:199], v[8:11]
	v_mfma_f32_16x16x32_bf16 v[4:7], v[164:167], v[226:229], v[4:7]
	v_mfma_f32_16x16x32_bf16 v[0:3], v[172:175], v[226:229], v[0:3]
	v_mfma_f32_16x16x32_bf16 v[44:47], v[168:171], v[184:187], v[44:47]
	v_mfma_f32_16x16x32_bf16 v[40:43], v[176:179], v[184:187], v[40:43]
	v_mfma_f32_16x16x32_bf16 v[28:31], v[168:171], v[192:195], v[28:31]
	v_mfma_f32_16x16x32_bf16 v[24:27], v[176:179], v[192:195], v[24:27]
	v_mfma_f32_16x16x32_bf16 v[12:15], v[168:171], v[222:225], v[12:15]
	v_mfma_f32_16x16x32_bf16 v[8:11], v[176:179], v[222:225], v[8:11]
	v_mfma_f32_16x16x32_bf16 v[4:7], v[168:171], v[230:233], v[4:7]
	v_mfma_f32_16x16x32_bf16 v[0:3], v[176:179], v[230:233], v[0:3]
	s_setprio 0
	s_barrier
; #define PG8_STAGE(bufoff, gbase, voff) do { _Pragma("unroll") for (int _i = 0; _i < 2; ++_i) \
;         __builtin_amdgcn_global_load_lds((const unsigned*)((const char*)(gbase) + (voff)[_i]), (PG8_LAS unsigned*)(lds + (bufoff) + ldsw + _i * 8192), 16, 0, 0); } while (0)
; #define PG8_LDA(dst, b, h) do { _Pragma("unroll") for (int m = 0; m < 4; ++m) _Pragma("unroll") for (int k = 0; k < 2; ++k) dst[m][k] = *(const PG8_LAS bf16x8*)(lds + PG8_SA(b, h) + aoff + m * 2048 + k * 1024); } while (0)
; #define PG8_LDB(dst, b, h) do { _Pragma("unroll") for (int n = 0; n < 2; ++n) _Pragma("unroll") for (int k = 0; k < 2; ++k) dst[n][k] = *(const PG8_LAS bf16x8*)(lds + PG8_SB(b, h) + boff + n * 2048 + k * 1024); } while (0)
; #define PG8_MMA(ai, bj, At, Bt) do { __builtin_amdgcn_s_setprio(1); _Pragma("unroll") for (int m = 0; m < 4; ++m) _Pragma("unroll") for (int n = 0; n < 2; ++n) _Pragma("unroll") for (int k = 0; k < 2; ++k) \
;         acc[ai][bj][m][n] = __builtin_amdgcn_mfma_f32_16x16x32_bf16(Bt[n][k], At[m][k], acc[ai][bj][m][n], 0, 0, 0); __builtin_amdgcn_s_setprio(0); } while (0)
; #define PG8_WAIT_V(n) asm volatile("s_waitcnt vmcnt(" #n ")" ::: "memory")
; #define PG8_WAIT_L(n) asm volatile("s_waitcnt lgkmcnt(" #n ")" ::: "memory")
; #define PG8_BAR __builtin_amdgcn_s_barrier()
; #define PG8_SCHED __builtin_amdgcn_sched_barrier(0)
; template <class Epi, class Sched, bool ALIGN_EPI = false, bool SP2 = false>
; __device__ __forceinline__ void gemm_phase(PG8_LAS unsigned char* lds, const Gemm g, const Sched& S, const Epi& E) {
;     ...
;             PG8_LDB(B0, 1, 0); PG8_LDB(B1, 1, 1); PG8_SCHED; PG8_LDA(At, 1, 0); PG8_STAGE(PG8_SA(0, 1), a2 + hstep, voffA);
;             PG8_WAIT_V(8); PG8_WAIT_L(0); PG8_BAR; PG8_MMA(0, 0, At, B0); PG8_MMA(0, 1, At, B1); PG8_BAR; PG8_SCHED;
;             PG8_LDA(At, 1, 1); PG8_STAGE(PG8_SB(1, 0), b3, voffB); PG8_STAGE(PG8_SB(1, 1), b3 + hstep, voffB); PG8_STAGE(PG8_SA(1, 0), a3, voffA);
;             PG8_WAIT_V(8); PG8_WAIT_L(0); PG8_BAR; PG8_MMA(1, 0, At, B0); PG8_MMA(1, 1, At, B1); PG8_BAR; PG8_SCHED;
	s_add_i32 s88, 0, 0x18000
	s_add_i32 s89, 0, 0x1c000
	v_add_u32_e32 v154, s88, v139
	v_add_u32_e32 v163, s89, v139
	ds_read_b128 v[142:145], v154
	ds_read_b128 v[146:149], v154 offset:1024
	ds_read_b128 v[150:153], v154 offset:2048
	ds_read_b128 v[154:157], v154 offset:3072
	ds_read_b128 v[164:167], v163
	ds_read_b128 v[168:171], v163 offset:1024
	ds_read_b128 v[172:175], v163 offset:2048
	ds_read_b128 v[176:179], v163 offset:3072
	s_add_u32 s52, s52, 0x80000
	s_addc_u32 s53, s53, 0
	s_mov_b32 m0, s56
	ds_read_b128 v[180:183], v141 offset:32768
	ds_read_b128 v[184:187], v141 offset:33792
	ds_read_b128 v[188:191], v141 offset:34816
	ds_read_b128 v[192:195], v141 offset:35840
	ds_read_b128 v[196:199], v141 offset:36864
	ds_read_b128 v[222:225], v141 offset:37888
	ds_read_b128 v[226:229], v141 offset:38912
	ds_read_b128 v[230:233], v141 offset:39936
	global_load_lds_dwordx4 v132, s[52:53]
	s_mov_b32 m0, s57
	s_nop 0
	global_load_lds_dwordx4 v130, s[52:53]
	s_waitcnt vmcnt(8)
	s_waitcnt lgkmcnt(0)
	s_barrier
	s_setprio 1
	s_waitcnt lgkmcnt(0)
	v_mfma_f32_16x16x32_bf16 v[124:127], v[142:145], v[180:183], v[124:127]
	v_mfma_f32_16x16x32_bf16 v[120:123], v[150:153], v[180:183], v[120:123]
	v_mfma_f32_16x16x32_bf16 v[116:119], v[142:145], v[188:191], v[116:119]
	v_mfma_f32_16x16x32_bf16 v[112:115], v[150:153], v[188:191], v[112:115]
	v_mfma_f32_16x16x32_bf16 v[100:103], v[142:145], v[196:199], v[100:103]
	v_mfma_f32_16x16x32_bf16 v[96:99], v[150:153], v[196:199], v[96:99]
	v_mfma_f32_16x16x32_bf16 v[84:87], v[142:145], v[226:229], v[84:87]
	v_mfma_f32_16x16x32_bf16 v[80:83], v[150:153], v[226:229], v[80:83]
	v_mfma_f32_16x16x32_bf16 v[124:127], v[146:149], v[184:187], v[124:127]
	v_mfma_f32_16x16x32_bf16 v[120:123], v[154:157], v[184:187], v[120:123]
	v_mfma_f32_16x16x32_bf16 v[116:119], v[146:149], v[192:195], v[116:119]
	v_mfma_f32_16x16x32_bf16 v[112:115], v[154:157], v[192:195], v[112:115]
	v_mfma_f32_16x16x32_bf16 v[100:103], v[146:149], v[222:225], v[100:103]
	v_mfma_f32_16x16x32_bf16 v[96:99], v[154:157], v[222:225], v[96:99]
	v_mfma_f32_16x16x32_bf16 v[84:87], v[146:149], v[230:233], v[84:87]
	v_mfma_f32_16x16x32_bf16 v[80:83], v[154:157], v[230:233], v[80:83]
	s_setprio 0
	s_setprio 1
	v_mfma_f32_16x16x32_bf16 v[108:111], v[164:167], v[180:183], v[108:111]
	v_mfma_f32_16x16x32_bf16 v[104:107], v[172:175], v[180:183], v[104:107]
	v_mfma_f32_16x16x32_bf16 v[92:95], v[164:167], v[188:191], v[92:95]
	v_mfma_f32_16x16x32_bf16 v[88:91], v[172:175], v[188:191], v[88:91]
	v_mfma_f32_16x16x32_bf16 v[76:79], v[164:167], v[196:199], v[76:79]
	v_mfma_f32_16x16x32_bf16 v[72:75], v[172:175], v[196:199], v[72:75]
	v_mfma_f32_16x16x32_bf16 v[68:71], v[164:167], v[226:229], v[68:71]
	v_mfma_f32_16x16x32_bf16 v[64:67], v[172:175], v[226:229], v[64:67]
	v_mfma_f32_16x16x32_bf16 v[108:111], v[168:171], v[184:187], v[108:111]
	v_mfma_f32_16x16x32_bf16 v[104:107], v[176:179], v[184:187], v[104:107]
	v_mfma_f32_16x16x32_bf16 v[92:95], v[168:171], v[192:195], v[92:95]
	v_mfma_f32_16x16x32_bf16 v[88:91], v[176:179], v[192:195], v[88:91]
	v_mfma_f32_16x16x32_bf16 v[76:79], v[168:171], v[222:225], v[76:79]
	v_mfma_f32_16x16x32_bf16 v[72:75], v[176:179], v[222:225], v[72:75]
	v_mfma_f32_16x16x32_bf16 v[68:71], v[168:171], v[230:233], v[68:71]
	v_mfma_f32_16x16x32_bf16 v[64:67], v[176:179], v[230:233], v[64:67]
	s_setprio 0
	s_barrier
	s_add_i32 s52, s88, s28
	s_mov_b32 m0, s52
	ds_read_b128 v[180:183], v141 offset:49152
	ds_read_b128 v[184:187], v141 offset:50176
	ds_read_b128 v[188:191], v141 offset:51200
	ds_read_b128 v[192:195], v141 offset:52224
	ds_read_b128 v[196:199], v141 offset:53248
	ds_read_b128 v[222:225], v141 offset:54272
	ds_read_b128 v[226:229], v141 offset:55296
	ds_read_b128 v[230:233], v141 offset:56320
	s_add_u32 s4, s4, 0x80
	s_addc_u32 s5, s5, 0
	global_load_lds_dwordx4 v160, s[4:5]
	s_add_i32 m0, s52, 0x2000
	s_add_i32 s52, s89, s28
	global_load_lds_dwordx4 v128, s[4:5]
	s_add_u32 s4, s4, 0x80000
	s_addc_u32 s5, s5, 0
	s_mov_b32 m0, s52
	s_nop 0
	global_load_lds_dwordx4 v160, s[4:5]
	s_add_i32 m0, s52, 0x2000
	s_nop 0
	global_load_lds_dwordx4 v128, s[4:5]
	s_mov_b32 m0, s24
	s_nop 0
	global_load_lds_dwordx4 v132, s[98:99]
	s_mov_b32 m0, s59
	s_nop 0
	global_load_lds_dwordx4 v130, s[98:99]
	s_waitcnt vmcnt(8)
	s_waitcnt lgkmcnt(0)
	s_barrier
	s_setprio 1
	s_waitcnt lgkmcnt(0)
	v_mfma_f32_16x16x32_bf16 v[60:63], v[142:145], v[180:183], v[60:63]
	v_mfma_f32_16x16x32_bf16 v[56:59], v[150:153], v[180:183], v[56:59]
	v_mfma_f32_16x16x32_bf16 v[52:55], v[142:145], v[188:191], v[52:55]
	v_mfma_f32_16x16x32_bf16 v[48:51], v[150:153], v[188:191], v[48:51]
	v_mfma_f32_16x16x32_bf16 v[36:39], v[142:145], v[196:199], v[36:39]
	v_mfma_f32_16x16x32_bf16 v[32:35], v[150:153], v[196:199], v[32:35]
	v_mfma_f32_16x16x32_bf16 v[20:23], v[142:145], v[226:229], v[20:23]
	v_mfma_f32_16x16x32_bf16 v[16:19], v[150:153], v[226:229], v[16:19]
	v_mfma_f32_16x16x32_bf16 v[60:63], v[146:149], v[184:187], v[60:63]
	v_mfma_f32_16x16x32_bf16 v[56:59], v[154:157], v[184:187], v[56:59]
	v_mfma_f32_16x16x32_bf16 v[52:55], v[146:149], v[192:195], v[52:55]
	v_mfma_f32_16x16x32_bf16 v[48:51], v[154:157], v[192:195], v[48:51]
	v_mfma_f32_16x16x32_bf16 v[36:39], v[146:149], v[222:225], v[36:39]
	v_mfma_f32_16x16x32_bf16 v[32:35], v[154:157], v[222:225], v[32:35]
	v_mfma_f32_16x16x32_bf16 v[20:23], v[146:149], v[230:233], v[20:23]
	v_mfma_f32_16x16x32_bf16 v[16:19], v[154:157], v[230:233], v[16:19]
	s_setprio 0
	s_setprio 1
	v_mfma_f32_16x16x32_bf16 v[44:47], v[164:167], v[180:183], v[44:47]
	v_mfma_f32_16x16x32_bf16 v[40:43], v[172:175], v[180:183], v[40:43]
	v_mfma_f32_16x16x32_bf16 v[28:31], v[164:167], v[188:191], v[28:31]
	v_mfma_f32_16x16x32_bf16 v[24:27], v[172:175], v[188:191], v[24:27]
	v_mfma_f32_16x16x32_bf16 v[12:15], v[164:167], v[196:199], v[12:15]
	v_mfma_f32_16x16x32_bf16 v[8:11], v[172:175], v[196:199], v[8:11]
	v_mfma_f32_16x16x32_bf16 v[4:7], v[164:167], v[226:229], v[4:7]
	v_mfma_f32_16x16x32_bf16 v[0:3], v[172:175], v[226:229], v[0:3]
	v_mfma_f32_16x16x32_bf16 v[44:47], v[168:171], v[184:187], v[44:47]
	v_mfma_f32_16x16x32_bf16 v[40:43], v[176:179], v[184:187], v[40:43]
	v_mfma_f32_16x16x32_bf16 v[28:31], v[168:171], v[192:195], v[28:31]
	v_mfma_f32_16x16x32_bf16 v[24:27], v[176:179], v[192:195], v[24:27]
	v_mfma_f32_16x16x32_bf16 v[12:15], v[168:171], v[222:225], v[12:15]
	v_mfma_f32_16x16x32_bf16 v[8:11], v[176:179], v[222:225], v[8:11]
	v_mfma_f32_16x16x32_bf16 v[4:7], v[168:171], v[230:233], v[4:7]
	v_mfma_f32_16x16x32_bf16 v[0:3], v[176:179], v[230:233], v[0:3]
	s_setprio 0
	s_barrier
	s_add_i32 s87, s87, 2
	s_add_u32 s80, s80, 0x100
	s_addc_u32 s81, s81, 0
	s_add_u32 s85, s85, 0x100
	s_addc_u32 s86, s86, 0
	s_cmp_gt_u32 s87, 29
	s_cbranch_scc0 .LBB0_25
	s_and_b64 vcc, exec, s[42:43]
	s_cbranch_vccz .LBB0_28
	s_barrier

; #define PG8_STAGE(bufoff, gbase, voff) do { _Pragma("unroll") for (int _i = 0; _i < 2; ++_i) \
;         __builtin_amdgcn_global_load_lds((const unsigned*)((const char*)(gbase) + (voff)[_i]), (PG8_LAS unsigned*)(lds + (bufoff) + ldsw + _i * 8192), 16, 0, 0); } while (0)
; #define PG8_LDA(dst, b, h) do { _Pragma("unroll") for (int m = 0; m < 4; ++m) _Pragma("unroll") for (int k = 0; k < 2; ++k) dst[m][k] = *(const PG8_LAS bf16x8*)(lds + PG8_SA(b, h) + aoff + m * 2048 + k * 1024); } while (0)
; #define PG8_LDB(dst, b, h) do { _Pragma("unroll") for (int n = 0; n < 2; ++n) _Pragma("unroll") for (int k = 0; k < 2; ++k) dst[n][k] = *(const PG8_LAS bf16x8*)(lds + PG8_SB(b, h) + boff + n * 2048 + k * 1024); } while (0)
; #define PG8_MMA(ai, bj, At, Bt) do { __builtin_amdgcn_s_setprio(1); _Pragma("unroll") for (int m = 0; m < 4; ++m) _Pragma("unroll") for (int n = 0; n < 2; ++n) _Pragma("unroll") for (int k = 0; k < 2; ++k) \
;         acc[ai][bj][m][n] = __builtin_amdgcn_mfma_f32_16x16x32_bf16(Bt[n][k], At[m][k], acc[ai][bj][m][n], 0, 0, 0); __builtin_amdgcn_s_setprio(0); } while (0)
; #define PG8_WAIT_V(n) asm volatile("s_waitcnt vmcnt(" #n ")" ::: "memory")
; #define PG8_WAIT_L(n) asm volatile("s_waitcnt lgkmcnt(" #n ")" ::: "memory")
; template <class Epi, class Sched, bool ALIGN_EPI = false, bool SP2 = false>
; __device__ __forceinline__ void gemm_phase(PG8_LAS unsigned char* lds, const Gemm g, const Sched& S, const Epi& E) {
;     ...
;             const bool last = (t == nt - 2);
;             const char* a1 = cA + (size_t)(t + 1) * kstep;
;             const char* a2 = last ? nA : cA + (size_t)(t + 2) * kstep; const char* b2 = last ? nB : cB + (size_t)(t + 2) * kstep;
;             const char* a3 = a2 + kstep; const char* b3 = b2 + kstep;
;             if (last && has_next) S.a_ready(nxt);
;             if constexpr (SP2) {
;             PG8_LDB(B0, 0, 0); PG8_LDB(B1, 0, 1); PG8_SCHED; PG8_LDA(At, 0, 0); PG8_STAGE(PG8_SA(1, 1), a1 + hstep, voffA);
;             PG8_WAIT_V(8); PG8_WAIT_L(0); PG8_BAR; PG8_MMA(0, 0, At, B0); PG8_MMA(0, 1, At, B1); PG8_BAR; PG8_SCHED;
;             PG8_LDA(At, 0, 1); PG8_STAGE(PG8_SB(0, 0), b2, voffB); PG8_STAGE(PG8_SB(0, 1), b2 + hstep, voffB); PG8_STAGE(PG8_SA(0, 0), a2, voffA);
;             PG8_WAIT_V(8); PG8_WAIT_L(0); PG8_BAR; PG8_MMA(1, 0, At, B0); PG8_MMA(1, 1, At, B1); PG8_BAR; PG8_SCHED;
.LBB0_52:
	s_add_i32 s84, 0, 0x10000
	s_add_i32 s85, 0, 0x14000
	v_add_u32_e32 v154, s84, v139
	v_add_u32_e32 v158, s85, v139
	ds_read_b128 v[142:145], v154
	ds_read_b128 v[146:149], v154 offset:1024
	ds_read_b128 v[150:153], v154 offset:2048
	ds_read_b128 v[154:157], v154 offset:3072
	ds_read_b128 v[164:167], v158
	ds_read_b128 v[168:171], v158 offset:1024
	ds_read_b128 v[172:175], v158 offset:2048
	ds_read_b128 v[176:179], v158 offset:3072
	s_add_i32 m0, s28, 0xc000
	ds_read_b128 v[180:183], v141
	ds_read_b128 v[184:187], v141 offset:1024
	ds_read_b128 v[188:191], v141 offset:2048
	ds_read_b128 v[192:195], v141 offset:3072
	ds_read_b128 v[196:199], v141 offset:4096
	ds_read_b128 v[222:225], v141 offset:5120
	ds_read_b128 v[226:229], v141 offset:6144
	ds_read_b128 v[230:233], v141 offset:7168
	global_load_lds_dwordx4 v134, s[72:73]
	s_add_i32 m0, s28, 0xe000
	s_nop 0
	global_load_lds_dwordx4 v136, s[72:73]
	s_add_u32 s4, s72, 0x100
	s_addc_u32 s5, s73, 0
	s_cmpk_eq_i32 s83, 0x54
	s_cselect_b32 s57, s45, s5
	s_cselect_b32 s56, s44, s4
	s_cselect_b32 s53, s55, s82
	s_cselect_b32 s52, s54, s81
	s_waitcnt vmcnt(8)
	s_waitcnt lgkmcnt(0)
	s_barrier
	s_setprio 1
	s_waitcnt lgkmcnt(0)
	v_mfma_f32_16x16x32_bf16 v[124:127], v[142:145], v[180:183], v[124:127]
	v_mfma_f32_16x16x32_bf16 v[120:123], v[150:153], v[180:183], v[120:123]
	v_mfma_f32_16x16x32_bf16 v[116:119], v[142:145], v[188:191], v[116:119]
	v_mfma_f32_16x16x32_bf16 v[112:115], v[150:153], v[188:191], v[112:115]
	v_mfma_f32_16x16x32_bf16 v[100:103], v[142:145], v[196:199], v[100:103]
	v_mfma_f32_16x16x32_bf16 v[96:99], v[150:153], v[196:199], v[96:99]
	v_mfma_f32_16x16x32_bf16 v[84:87], v[142:145], v[226:229], v[84:87]
	v_mfma_f32_16x16x32_bf16 v[80:83], v[150:153], v[226:229], v[80:83]
	v_mfma_f32_16x16x32_bf16 v[124:127], v[146:149], v[184:187], v[124:127]
	v_mfma_f32_16x16x32_bf16 v[120:123], v[154:157], v[184:187], v[120:123]
	v_mfma_f32_16x16x32_bf16 v[116:119], v[146:149], v[192:195], v[116:119]
	v_mfma_f32_16x16x32_bf16 v[112:115], v[154:157], v[192:195], v[112:115]
	v_mfma_f32_16x16x32_bf16 v[100:103], v[146:149], v[222:225], v[100:103]
	v_mfma_f32_16x16x32_bf16 v[96:99], v[154:157], v[222:225], v[96:99]
	v_mfma_f32_16x16x32_bf16 v[84:87], v[146:149], v[230:233], v[84:87]
	v_mfma_f32_16x16x32_bf16 v[80:83], v[154:157], v[230:233], v[80:83]
	s_setprio 0
	s_setprio 1
	v_mfma_f32_16x16x32_bf16 v[108:111], v[164:167], v[180:183], v[108:111]
	v_mfma_f32_16x16x32_bf16 v[104:107], v[172:175], v[180:183], v[104:107]
	v_mfma_f32_16x16x32_bf16 v[92:95], v[164:167], v[188:191], v[92:95]
	v_mfma_f32_16x16x32_bf16 v[88:91], v[172:175], v[188:191], v[88:91]
	v_mfma_f32_16x16x32_bf16 v[76:79], v[164:167], v[196:199], v[76:79]
	v_mfma_f32_16x16x32_bf16 v[72:75], v[172:175], v[196:199], v[72:75]
	v_mfma_f32_16x16x32_bf16 v[68:71], v[164:167], v[226:229], v[68:71]
	v_mfma_f32_16x16x32_bf16 v[64:67], v[172:175], v[226:229], v[64:67]
	v_mfma_f32_16x16x32_bf16 v[108:111], v[168:171], v[184:187], v[108:111]
	v_mfma_f32_16x16x32_bf16 v[104:107], v[176:179], v[184:187], v[104:107]
	v_mfma_f32_16x16x32_bf16 v[92:95], v[168:171], v[192:195], v[92:95]
	v_mfma_f32_16x16x32_bf16 v[88:91], v[176:179], v[192:195], v[88:91]
	v_mfma_f32_16x16x32_bf16 v[76:79], v[168:171], v[222:225], v[76:79]
	v_mfma_f32_16x16x32_bf16 v[72:75], v[176:179], v[222:225], v[72:75]
	v_mfma_f32_16x16x32_bf16 v[68:71], v[168:171], v[230:233], v[68:71]
	v_mfma_f32_16x16x32_bf16 v[64:67], v[176:179], v[230:233], v[64:67]
	s_setprio 0
	s_barrier
	s_add_i32 s72, s84, s24
	s_mov_b32 m0, s72
	ds_read_b128 v[180:183], v141 offset:16384
	ds_read_b128 v[184:187], v141 offset:17408
	ds_read_b128 v[188:191], v141 offset:18432
	ds_read_b128 v[192:195], v141 offset:19456
	ds_read_b128 v[196:199], v141 offset:20480
	ds_read_b128 v[222:225], v141 offset:21504
	ds_read_b128 v[226:229], v141 offset:22528
	ds_read_b128 v[230:233], v141 offset:23552
	global_load_lds_dwordx4 v160, s[52:53]
	s_add_i32 m0, s72, 0x2000
	s_add_u32 s72, s52, 0x160000
	s_addc_u32 s73, s53, 0
	s_add_i32 s84, s85, s24
	global_load_lds_dwordx4 v128, s[52:53]
	s_mov_b32 m0, s84
	s_nop 0
	global_load_lds_dwordx4 v160, s[72:73]
	s_add_i32 m0, s84, 0x2000
	s_nop 0
	global_load_lds_dwordx4 v128, s[72:73]
	s_mov_b32 m0, s28
	s_nop 0
	global_load_lds_dwordx4 v132, s[56:57]
	s_mov_b32 m0, s29
	s_nop 0
	global_load_lds_dwordx4 v130, s[56:57]
	s_add_u32 s98, s56, 0x80
	s_addc_u32 s99, s57, 0
	s_waitcnt vmcnt(8)
	s_waitcnt lgkmcnt(0)
	s_barrier
	s_setprio 1
	s_waitcnt lgkmcnt(0)
	v_mfma_f32_16x16x32_bf16 v[60:63], v[142:145], v[180:183], v[60:63]
	v_mfma_f32_16x16x32_bf16 v[56:59], v[150:153], v[180:183], v[56:59]
	v_mfma_f32_16x16x32_bf16 v[52:55], v[142:145], v[188:191], v[52:55]
	v_mfma_f32_16x16x32_bf16 v[48:51], v[150:153], v[188:191], v[48:51]
	v_mfma_f32_16x16x32_bf16 v[36:39], v[142:145], v[196:199], v[36:39]
	v_mfma_f32_16x16x32_bf16 v[32:35], v[150:153], v[196:199], v[32:35]
	v_mfma_f32_16x16x32_bf16 v[20:23], v[142:145], v[226:229], v[20:23]
	v_mfma_f32_16x16x32_bf16 v[16:19], v[150:153], v[226:229], v[16:19]
	v_mfma_f32_16x16x32_bf16 v[60:63], v[146:149], v[184:187], v[60:63]
	v_mfma_f32_16x16x32_bf16 v[56:59], v[154:157], v[184:187], v[56:59]
	v_mfma_f32_16x16x32_bf16 v[52:55], v[146:149], v[192:195], v[52:55]
	v_mfma_f32_16x16x32_bf16 v[48:51], v[154:157], v[192:195], v[48:51]
	v_mfma_f32_16x16x32_bf16 v[36:39], v[146:149], v[222:225], v[36:39]
	v_mfma_f32_16x16x32_bf16 v[32:35], v[154:157], v[222:225], v[32:35]
	v_mfma_f32_16x16x32_bf16 v[20:23], v[146:149], v[230:233], v[20:23]
	v_mfma_f32_16x16x32_bf16 v[16:19], v[154:157], v[230:233], v[16:19]
	s_setprio 0
	s_setprio 1
	v_mfma_f32_16x16x32_bf16 v[44:47], v[164:167], v[180:183], v[44:47]
	v_mfma_f32_16x16x32_bf16 v[40:43], v[172:175], v[180:183], v[40:43]
	v_mfma_f32_16x16x32_bf16 v[28:31], v[164:167], v[188:191], v[28:31]
	v_mfma_f32_16x16x32_bf16 v[24:27], v[172:175], v[188:191], v[24:27]
	v_mfma_f32_16x16x32_bf16 v[12:15], v[164:167], v[196:199], v[12:15]
	v_mfma_f32_16x16x32_bf16 v[8:11], v[172:175], v[196:199], v[8:11]
	v_mfma_f32_16x16x32_bf16 v[4:7], v[164:167], v[226:229], v[4:7]
	v_mfma_f32_16x16x32_bf16 v[0:3], v[172:175], v[226:229], v[0:3]
	v_mfma_f32_16x16x32_bf16 v[44:47], v[168:171], v[184:187], v[44:47]
	v_mfma_f32_16x16x32_bf16 v[40:43], v[176:179], v[184:187], v[40:43]
	v_mfma_f32_16x16x32_bf16 v[28:31], v[168:171], v[192:195], v[28:31]
	v_mfma_f32_16x16x32_bf16 v[24:27], v[176:179], v[192:195], v[24:27]
	v_mfma_f32_16x16x32_bf16 v[12:15], v[168:171], v[222:225], v[12:15]
	v_mfma_f32_16x16x32_bf16 v[8:11], v[176:179], v[222:225], v[8:11]
	v_mfma_f32_16x16x32_bf16 v[4:7], v[168:171], v[230:233], v[4:7]
	v_mfma_f32_16x16x32_bf16 v[0:3], v[176:179], v[230:233], v[0:3]
	s_setprio 0
	s_barrier
; #define PG8_STAGE(bufoff, gbase, voff) do { _Pragma("unroll") for (int _i = 0; _i < 2; ++_i) \
;         __builtin_amdgcn_global_load_lds((const unsigned*)((const char*)(gbase) + (voff)[_i]), (PG8_LAS unsigned*)(lds + (bufoff) + ldsw + _i * 8192), 16, 0, 0); } while (0)
; #define PG8_LDA(dst, b, h) do { _Pragma("unroll") for (int m = 0; m < 4; ++m) _Pragma("unroll") for (int k = 0; k < 2; ++k) dst[m][k] = *(const PG8_LAS bf16x8*)(lds + PG8_SA(b, h) + aoff + m * 2048 + k * 1024); } while (0)
; #define PG8_LDB(dst, b, h) do { _Pragma("unroll") for (int n = 0; n < 2; ++n) _Pragma("unroll") for (int k = 0; k < 2; ++k) dst[n][k] = *(const PG8_LAS bf16x8*)(lds + PG8_SB(b, h) + boff + n * 2048 + k * 1024); } while (0)
; #define PG8_MMA(ai, bj, At, Bt) do { __builtin_amdgcn_s_setprio(1); _Pragma("unroll") for (int m = 0; m < 4; ++m) _Pragma("unroll") for (int n = 0; n < 2; ++n) _Pragma("unroll") for (int k = 0; k < 2; ++k) \
;         acc[ai][bj][m][n] = __builtin_amdgcn_mfma_f32_16x16x32_bf16(Bt[n][k], At[m][k], acc[ai][bj][m][n], 0, 0, 0); __builtin_amdgcn_s_setprio(0); } while (0)
; #define PG8_WAIT_V(n) asm volatile("s_waitcnt vmcnt(" #n ")" ::: "memory")
; #define PG8_WAIT_L(n) asm volatile("s_waitcnt lgkmcnt(" #n ")" ::: "memory")
; #define PG8_BAR __builtin_amdgcn_s_barrier()
; #define PG8_SCHED __builtin_amdgcn_sched_barrier(0)
; template <class Epi, class Sched, bool ALIGN_EPI = false, bool SP2 = false>
; __device__ __forceinline__ void gemm_phase(PG8_LAS unsigned char* lds, const Gemm g, const Sched& S, const Epi& E) {
;     ...
;             PG8_LDB(B0, 1, 0); PG8_LDB(B1, 1, 1); PG8_SCHED; PG8_LDA(At, 1, 0); PG8_STAGE(PG8_SA(0, 1), a2 + hstep, voffA);
;             PG8_WAIT_V(8); PG8_WAIT_L(0); PG8_BAR; PG8_MMA(0, 0, At, B0); PG8_MMA(0, 1, At, B1); PG8_BAR; PG8_SCHED;
;             PG8_LDA(At, 1, 1); PG8_STAGE(PG8_SB(1, 0), b3, voffB); PG8_STAGE(PG8_SB(1, 1), b3 + hstep, voffB); PG8_STAGE(PG8_SA(1, 0), a3, voffA);
;             PG8_WAIT_V(8); PG8_WAIT_L(0); PG8_BAR; PG8_MMA(1, 0, At, B0); PG8_MMA(1, 1, At, B1); PG8_BAR; PG8_SCHED;
	s_add_i32 s72, 0, 0x18000
	s_add_i32 s73, 0, 0x1c000
	v_add_u32_e32 v154, s72, v139
	v_add_u32_e32 v163, s73, v139
	ds_read_b128 v[142:145], v154
	ds_read_b128 v[146:149], v154 offset:1024
	ds_read_b128 v[150:153], v154 offset:2048
	ds_read_b128 v[154:157], v154 offset:3072
	ds_read_b128 v[164:167], v163
	ds_read_b128 v[168:171], v163 offset:1024
	ds_read_b128 v[172:175], v163 offset:2048
	ds_read_b128 v[176:179], v163 offset:3072
	s_add_u32 s56, s56, 0x160000
	s_addc_u32 s57, s57, 0
	s_mov_b32 m0, s59
	ds_read_b128 v[180:183], v141 offset:32768
	ds_read_b128 v[184:187], v141 offset:33792
	ds_read_b128 v[188:191], v141 offset:34816
	ds_read_b128 v[192:195], v141 offset:35840
	ds_read_b128 v[196:199], v141 offset:36864
	ds_read_b128 v[222:225], v141 offset:37888
	ds_read_b128 v[226:229], v141 offset:38912
	ds_read_b128 v[230:233], v141 offset:39936
	global_load_lds_dwordx4 v132, s[56:57]
	s_mov_b32 m0, s63
	s_nop 0
	global_load_lds_dwordx4 v130, s[56:57]
	s_waitcnt vmcnt(8)
	s_waitcnt lgkmcnt(0)
	s_barrier
	s_setprio 1
	s_waitcnt lgkmcnt(0)
	v_mfma_f32_16x16x32_bf16 v[124:127], v[142:145], v[180:183], v[124:127]
	v_mfma_f32_16x16x32_bf16 v[120:123], v[150:153], v[180:183], v[120:123]
	v_mfma_f32_16x16x32_bf16 v[116:119], v[142:145], v[188:191], v[116:119]
	v_mfma_f32_16x16x32_bf16 v[112:115], v[150:153], v[188:191], v[112:115]
	v_mfma_f32_16x16x32_bf16 v[100:103], v[142:145], v[196:199], v[100:103]
	v_mfma_f32_16x16x32_bf16 v[96:99], v[150:153], v[196:199], v[96:99]
	v_mfma_f32_16x16x32_bf16 v[84:87], v[142:145], v[226:229], v[84:87]
	v_mfma_f32_16x16x32_bf16 v[80:83], v[150:153], v[226:229], v[80:83]
	v_mfma_f32_16x16x32_bf16 v[124:127], v[146:149], v[184:187], v[124:127]
	v_mfma_f32_16x16x32_bf16 v[120:123], v[154:157], v[184:187], v[120:123]
	v_mfma_f32_16x16x32_bf16 v[116:119], v[146:149], v[192:195], v[116:119]
	v_mfma_f32_16x16x32_bf16 v[112:115], v[154:157], v[192:195], v[112:115]
	v_mfma_f32_16x16x32_bf16 v[100:103], v[146:149], v[222:225], v[100:103]
	v_mfma_f32_16x16x32_bf16 v[96:99], v[154:157], v[222:225], v[96:99]
	v_mfma_f32_16x16x32_bf16 v[84:87], v[146:149], v[230:233], v[84:87]
	v_mfma_f32_16x16x32_bf16 v[80:83], v[154:157], v[230:233], v[80:83]
	s_setprio 0
	s_setprio 1
	v_mfma_f32_16x16x32_bf16 v[108:111], v[164:167], v[180:183], v[108:111]
	v_mfma_f32_16x16x32_bf16 v[104:107], v[172:175], v[180:183], v[104:107]
	v_mfma_f32_16x16x32_bf16 v[92:95], v[164:167], v[188:191], v[92:95]
	v_mfma_f32_16x16x32_bf16 v[88:91], v[172:175], v[188:191], v[88:91]
	v_mfma_f32_16x16x32_bf16 v[76:79], v[164:167], v[196:199], v[76:79]
	v_mfma_f32_16x16x32_bf16 v[72:75], v[172:175], v[196:199], v[72:75]
	v_mfma_f32_16x16x32_bf16 v[68:71], v[164:167], v[226:229], v[68:71]
	v_mfma_f32_16x16x32_bf16 v[64:67], v[172:175], v[226:229], v[64:67]
	v_mfma_f32_16x16x32_bf16 v[108:111], v[168:171], v[184:187], v[108:111]
	v_mfma_f32_16x16x32_bf16 v[104:107], v[176:179], v[184:187], v[104:107]
	v_mfma_f32_16x16x32_bf16 v[92:95], v[168:171], v[192:195], v[92:95]
	v_mfma_f32_16x16x32_bf16 v[88:91], v[176:179], v[192:195], v[88:91]
	v_mfma_f32_16x16x32_bf16 v[76:79], v[168:171], v[222:225], v[76:79]
	v_mfma_f32_16x16x32_bf16 v[72:75], v[176:179], v[222:225], v[72:75]
	v_mfma_f32_16x16x32_bf16 v[68:71], v[168:171], v[230:233], v[68:71]
	v_mfma_f32_16x16x32_bf16 v[64:67], v[176:179], v[230:233], v[64:67]
	s_setprio 0
	s_barrier
	s_add_i32 s56, s72, s24
	s_mov_b32 m0, s56
	ds_read_b128 v[180:183], v141 offset:49152
	ds_read_b128 v[184:187], v141 offset:50176
	ds_read_b128 v[188:191], v141 offset:51200
	ds_read_b128 v[192:195], v141 offset:52224
	ds_read_b128 v[196:199], v141 offset:53248
	ds_read_b128 v[222:225], v141 offset:54272
	ds_read_b128 v[226:229], v141 offset:55296
	ds_read_b128 v[230:233], v141 offset:56320
	s_add_u32 s52, s52, 0x80
	s_addc_u32 s53, s53, 0
	global_load_lds_dwordx4 v160, s[52:53]
	s_add_i32 m0, s56, 0x2000
	s_add_i32 s56, s73, s24
	global_load_lds_dwordx4 v128, s[52:53]
	s_add_u32 s52, s52, 0x160000
	s_addc_u32 s53, s53, 0
	s_mov_b32 m0, s56
	s_nop 0
	global_load_lds_dwordx4 v160, s[52:53]
	s_add_i32 m0, s56, 0x2000
	s_nop 0
	global_load_lds_dwordx4 v128, s[52:53]
	s_mov_b32 m0, s74
	s_nop 0
	global_load_lds_dwordx4 v132, s[98:99]
	s_mov_b32 m0, s75
	s_nop 0
	global_load_lds_dwordx4 v130, s[98:99]
	s_waitcnt vmcnt(8)
	s_waitcnt lgkmcnt(0)
	s_barrier
	s_setprio 1
	s_waitcnt lgkmcnt(0)
	v_mfma_f32_16x16x32_bf16 v[60:63], v[142:145], v[180:183], v[60:63]
	v_mfma_f32_16x16x32_bf16 v[56:59], v[150:153], v[180:183], v[56:59]
	v_mfma_f32_16x16x32_bf16 v[52:55], v[142:145], v[188:191], v[52:55]
	v_mfma_f32_16x16x32_bf16 v[48:51], v[150:153], v[188:191], v[48:51]
	v_mfma_f32_16x16x32_bf16 v[36:39], v[142:145], v[196:199], v[36:39]
	v_mfma_f32_16x16x32_bf16 v[32:35], v[150:153], v[196:199], v[32:35]
	v_mfma_f32_16x16x32_bf16 v[20:23], v[142:145], v[226:229], v[20:23]
	v_mfma_f32_16x16x32_bf16 v[16:19], v[150:153], v[226:229], v[16:19]
	v_mfma_f32_16x16x32_bf16 v[60:63], v[146:149], v[184:187], v[60:63]
	v_mfma_f32_16x16x32_bf16 v[56:59], v[154:157], v[184:187], v[56:59]
	v_mfma_f32_16x16x32_bf16 v[52:55], v[146:149], v[192:195], v[52:55]
	v_mfma_f32_16x16x32_bf16 v[48:51], v[154:157], v[192:195], v[48:51]
	v_mfma_f32_16x16x32_bf16 v[36:39], v[146:149], v[222:225], v[36:39]
	v_mfma_f32_16x16x32_bf16 v[32:35], v[154:157], v[222:225], v[32:35]
	v_mfma_f32_16x16x32_bf16 v[20:23], v[146:149], v[230:233], v[20:23]
	v_mfma_f32_16x16x32_bf16 v[16:19], v[154:157], v[230:233], v[16:19]
	s_setprio 0
	s_setprio 1
	v_mfma_f32_16x16x32_bf16 v[44:47], v[164:167], v[180:183], v[44:47]
	v_mfma_f32_16x16x32_bf16 v[40:43], v[172:175], v[180:183], v[40:43]
	v_mfma_f32_16x16x32_bf16 v[28:31], v[164:167], v[188:191], v[28:31]
	v_mfma_f32_16x16x32_bf16 v[24:27], v[172:175], v[188:191], v[24:27]
	v_mfma_f32_16x16x32_bf16 v[12:15], v[164:167], v[196:199], v[12:15]
	v_mfma_f32_16x16x32_bf16 v[8:11], v[172:175], v[196:199], v[8:11]
	v_mfma_f32_16x16x32_bf16 v[4:7], v[164:167], v[226:229], v[4:7]
	v_mfma_f32_16x16x32_bf16 v[0:3], v[172:175], v[226:229], v[0:3]
	v_mfma_f32_16x16x32_bf16 v[44:47], v[168:171], v[184:187], v[44:47]
	v_mfma_f32_16x16x32_bf16 v[40:43], v[176:179], v[184:187], v[40:43]
	v_mfma_f32_16x16x32_bf16 v[28:31], v[168:171], v[192:195], v[28:31]
	v_mfma_f32_16x16x32_bf16 v[24:27], v[176:179], v[192:195], v[24:27]
	v_mfma_f32_16x16x32_bf16 v[12:15], v[168:171], v[222:225], v[12:15]
	v_mfma_f32_16x16x32_bf16 v[8:11], v[176:179], v[222:225], v[8:11]
	v_mfma_f32_16x16x32_bf16 v[4:7], v[168:171], v[230:233], v[4:7]
	v_mfma_f32_16x16x32_bf16 v[0:3], v[176:179], v[230:233], v[0:3]
	s_setprio 0
	s_barrier
	s_add_i32 s83, s83, 2
	s_add_u32 s81, s81, 0x100
	s_addc_u32 s82, s82, 0
	s_cmpk_gt_u32 s83, 0x55
	s_mov_b64 s[72:73], s[4:5]
	s_cbranch_scc0 .LBB0_52
	s_and_b64 vcc, exec, s[42:43]
	s_cbranch_vccz .LBB0_55
	s_barrier

; #define PG8_STAGE(bufoff, gbase, voff) do { _Pragma("unroll") for (int _i = 0; _i < 2; ++_i) \
;         __builtin_amdgcn_global_load_lds((const unsigned*)((const char*)(gbase) + (voff)[_i]), (PG8_LAS unsigned*)(lds + (bufoff) + ldsw + _i * 8192), 16, 0, 0); } while (0)
; #define PG8_LDA(dst, b, h) do { _Pragma("unroll") for (int m = 0; m < 4; ++m) _Pragma("unroll") for (int k = 0; k < 2; ++k) dst[m][k] = *(const PG8_LAS bf16x8*)(lds + PG8_SA(b, h) + aoff + m * 2048 + k * 1024); } while (0)
; #define PG8_LDB(dst, b, h) do { _Pragma("unroll") for (int n = 0; n < 2; ++n) _Pragma("unroll") for (int k = 0; k < 2; ++k) dst[n][k] = *(const PG8_LAS bf16x8*)(lds + PG8_SB(b, h) + boff + n * 2048 + k * 1024); } while (0)
; #define PG8_MMA(ai, bj, At, Bt) do { __builtin_amdgcn_s_setprio(1); _Pragma("unroll") for (int m = 0; m < 4; ++m) _Pragma("unroll") for (int n = 0; n < 2; ++n) _Pragma("unroll") for (int k = 0; k < 2; ++k) \
;         acc[ai][bj][m][n] = __builtin_amdgcn_mfma_f32_16x16x32_bf16(Bt[n][k], At[m][k], acc[ai][bj][m][n], 0, 0, 0); __builtin_amdgcn_s_setprio(0); } while (0)
; #define PG8_WAIT_V(n) asm volatile("s_waitcnt vmcnt(" #n ")" ::: "memory")
; #define PG8_WAIT_L(n) asm volatile("s_waitcnt lgkmcnt(" #n ")" ::: "memory")
; template <class Epi, class Sched, bool ALIGN_EPI = false, bool SP2 = false>
; __device__ __forceinline__ void gemm_phase(PG8_LAS unsigned char* lds, const Gemm g, const Sched& S, const Epi& E) {
;     ...
;             const bool last = (t == nt - 2);
;             const char* a1 = cA + (size_t)(t + 1) * kstep;
;             const char* a2 = last ? nA : cA + (size_t)(t + 2) * kstep; const char* b2 = last ? nB : cB + (size_t)(t + 2) * kstep;
;             const char* a3 = a2 + kstep; const char* b3 = b2 + kstep;
;             if (last && has_next) S.a_ready(nxt);
;             if constexpr (SP2) {
;             PG8_LDB(B0, 0, 0); PG8_LDB(B1, 0, 1); PG8_SCHED; PG8_LDA(At, 0, 0); PG8_STAGE(PG8_SA(1, 1), a1 + hstep, voffA);
;             PG8_WAIT_V(8); PG8_WAIT_L(0); PG8_BAR; PG8_MMA(0, 0, At, B0); PG8_MMA(0, 1, At, B1); PG8_BAR; PG8_SCHED;
;             PG8_LDA(At, 0, 1); PG8_STAGE(PG8_SB(0, 0), b2, voffB); PG8_STAGE(PG8_SB(0, 1), b2 + hstep, voffB); PG8_STAGE(PG8_SA(0, 0), a2, voffA);
;             PG8_WAIT_V(8); PG8_WAIT_L(0); PG8_BAR; PG8_MMA(1, 0, At, B0); PG8_MMA(1, 1, At, B1); PG8_BAR; PG8_SCHED;
.LBB0_86:
	s_add_i32 s88, 0, 0x10000
	v_add_u32_e32 v144, s88, v147
	s_add_i32 s90, 0, 0x14000
	ds_read_b128 v[140:143], v144
	ds_read_b128 v[150:153], v144 offset:1024
	ds_read_b128 v[154:157], v144 offset:2048
	ds_read_b128 v[164:167], v144 offset:3072
	v_add_u32_e32 v144, s90, v147
	ds_read_b128 v[168:171], v144
	ds_read_b128 v[172:175], v144 offset:1024
	ds_read_b128 v[176:179], v144 offset:2048
	ds_read_b128 v[180:183], v144 offset:3072
	s_add_i32 m0, s63, 0xc000
	ds_read_b128 v[184:187], v149
	ds_read_b128 v[188:191], v149 offset:1024
	ds_read_b128 v[192:195], v149 offset:2048
	ds_read_b128 v[196:199], v149 offset:3072
	ds_read_b128 v[222:225], v149 offset:4096
	ds_read_b128 v[226:229], v149 offset:5120
	ds_read_b128 v[230:233], v149 offset:6144
	ds_read_b128 v[234:237], v149 offset:7168
	global_load_lds_dwordx4 v136, s[82:83]
	s_add_i32 m0, s63, 0xe000
	s_nop 0
	global_load_lds_dwordx4 v138, s[82:83]
	s_add_u32 s4, s82, 0xfffc0080
	s_addc_u32 s5, s83, -1
	s_cmp_eq_u32 s87, 12
	s_cselect_b32 s53, s7, s5
	s_cselect_b32 s52, s15, s4
	s_cselect_b32 s5, s24, s43
	s_cselect_b32 s4, s28, s29
	s_waitcnt vmcnt(8)
	s_waitcnt lgkmcnt(0)
	s_barrier
	s_setprio 1
	s_waitcnt lgkmcnt(0)
	v_mfma_f32_16x16x32_bf16 v[124:127], v[140:143], v[184:187], v[124:127]
	v_mfma_f32_16x16x32_bf16 v[120:123], v[154:157], v[184:187], v[120:123]
	v_mfma_f32_16x16x32_bf16 v[108:111], v[140:143], v[192:195], v[108:111]
	v_mfma_f32_16x16x32_bf16 v[104:107], v[154:157], v[192:195], v[104:107]
	v_mfma_f32_16x16x32_bf16 v[92:95], v[140:143], v[222:225], v[92:95]
	v_mfma_f32_16x16x32_bf16 v[88:91], v[154:157], v[222:225], v[88:91]
	v_mfma_f32_16x16x32_bf16 v[76:79], v[140:143], v[230:233], v[76:79]
	v_mfma_f32_16x16x32_bf16 v[72:75], v[154:157], v[230:233], v[72:75]
	v_mfma_f32_16x16x32_bf16 v[124:127], v[150:153], v[188:191], v[124:127]
	v_mfma_f32_16x16x32_bf16 v[120:123], v[164:167], v[188:191], v[120:123]
	v_mfma_f32_16x16x32_bf16 v[108:111], v[150:153], v[196:199], v[108:111]
	v_mfma_f32_16x16x32_bf16 v[104:107], v[164:167], v[196:199], v[104:107]
	v_mfma_f32_16x16x32_bf16 v[92:95], v[150:153], v[226:229], v[92:95]
	v_mfma_f32_16x16x32_bf16 v[88:91], v[164:167], v[226:229], v[88:91]
	v_mfma_f32_16x16x32_bf16 v[76:79], v[150:153], v[234:237], v[76:79]
	v_mfma_f32_16x16x32_bf16 v[72:75], v[164:167], v[234:237], v[72:75]
	s_setprio 0
	s_setprio 1
	v_mfma_f32_16x16x32_bf16 v[116:119], v[168:171], v[184:187], v[116:119]
	v_mfma_f32_16x16x32_bf16 v[112:115], v[176:179], v[184:187], v[112:115]
	v_mfma_f32_16x16x32_bf16 v[100:103], v[168:171], v[192:195], v[100:103]
	v_mfma_f32_16x16x32_bf16 v[96:99], v[176:179], v[192:195], v[96:99]
	v_mfma_f32_16x16x32_bf16 v[84:87], v[168:171], v[222:225], v[84:87]
	v_mfma_f32_16x16x32_bf16 v[80:83], v[176:179], v[222:225], v[80:83]
	v_mfma_f32_16x16x32_bf16 v[68:71], v[168:171], v[230:233], v[68:71]
	v_mfma_f32_16x16x32_bf16 v[64:67], v[176:179], v[230:233], v[64:67]
	v_mfma_f32_16x16x32_bf16 v[116:119], v[172:175], v[188:191], v[116:119]
	v_mfma_f32_16x16x32_bf16 v[112:115], v[180:183], v[188:191], v[112:115]
	v_mfma_f32_16x16x32_bf16 v[100:103], v[172:175], v[196:199], v[100:103]
	v_mfma_f32_16x16x32_bf16 v[96:99], v[180:183], v[196:199], v[96:99]
	v_mfma_f32_16x16x32_bf16 v[84:87], v[172:175], v[226:229], v[84:87]
	v_mfma_f32_16x16x32_bf16 v[80:83], v[180:183], v[226:229], v[80:83]
	v_mfma_f32_16x16x32_bf16 v[68:71], v[172:175], v[234:237], v[68:71]
	v_mfma_f32_16x16x32_bf16 v[64:67], v[180:183], v[234:237], v[64:67]
	s_setprio 0
	s_barrier
	s_add_i32 s88, s88, s59
	s_mov_b32 m0, s88
	ds_read_b128 v[184:187], v149 offset:16384
	ds_read_b128 v[188:191], v149 offset:17408
	ds_read_b128 v[192:195], v149 offset:18432
	ds_read_b128 v[196:199], v149 offset:19456
	ds_read_b128 v[222:225], v149 offset:20480
	ds_read_b128 v[226:229], v149 offset:21504
	ds_read_b128 v[230:233], v149 offset:22528
	ds_read_b128 v[234:237], v149 offset:23552
	global_load_lds_dwordx4 v130, s[4:5]
	s_add_i32 m0, s88, 0x2000
	s_add_u32 s88, s4, 0x40000
	s_addc_u32 s89, s5, 0
	s_add_i32 s90, s90, s59
	global_load_lds_dwordx4 v134, s[4:5]
	s_mov_b32 m0, s90
	s_nop 0
	global_load_lds_dwordx4 v130, s[88:89]
	s_add_i32 m0, s90, 0x2000
	s_nop 0
	global_load_lds_dwordx4 v134, s[88:89]
	s_mov_b32 m0, s63
	s_nop 0
	global_load_lds_dwordx4 v128, s[52:53]
	s_mov_b32 m0, s74
	s_nop 0
	global_load_lds_dwordx4 v132, s[52:53]
	s_add_u32 s98, s52, 0x80
	s_addc_u32 s99, s53, 0
	s_waitcnt vmcnt(8)
	s_waitcnt lgkmcnt(0)
	s_barrier
	s_setprio 1
	s_waitcnt lgkmcnt(0)
	v_mfma_f32_16x16x32_bf16 v[60:63], v[140:143], v[184:187], v[60:63]
	v_mfma_f32_16x16x32_bf16 v[56:59], v[154:157], v[184:187], v[56:59]
	v_mfma_f32_16x16x32_bf16 v[44:47], v[140:143], v[192:195], v[44:47]
	v_mfma_f32_16x16x32_bf16 v[40:43], v[154:157], v[192:195], v[40:43]
	v_mfma_f32_16x16x32_bf16 v[28:31], v[140:143], v[222:225], v[28:31]
	v_mfma_f32_16x16x32_bf16 v[24:27], v[154:157], v[222:225], v[24:27]
	v_mfma_f32_16x16x32_bf16 v[12:15], v[140:143], v[230:233], v[12:15]
	v_mfma_f32_16x16x32_bf16 v[8:11], v[154:157], v[230:233], v[8:11]
	v_mfma_f32_16x16x32_bf16 v[60:63], v[150:153], v[188:191], v[60:63]
	v_mfma_f32_16x16x32_bf16 v[56:59], v[164:167], v[188:191], v[56:59]
	v_mfma_f32_16x16x32_bf16 v[44:47], v[150:153], v[196:199], v[44:47]
	v_mfma_f32_16x16x32_bf16 v[40:43], v[164:167], v[196:199], v[40:43]
	v_mfma_f32_16x16x32_bf16 v[28:31], v[150:153], v[226:229], v[28:31]
	v_mfma_f32_16x16x32_bf16 v[24:27], v[164:167], v[226:229], v[24:27]
	v_mfma_f32_16x16x32_bf16 v[12:15], v[150:153], v[234:237], v[12:15]
	v_mfma_f32_16x16x32_bf16 v[8:11], v[164:167], v[234:237], v[8:11]
	s_setprio 0
	s_setprio 1
	v_mfma_f32_16x16x32_bf16 v[52:55], v[168:171], v[184:187], v[52:55]
	v_mfma_f32_16x16x32_bf16 v[48:51], v[176:179], v[184:187], v[48:51]
	v_mfma_f32_16x16x32_bf16 v[36:39], v[168:171], v[192:195], v[36:39]
	v_mfma_f32_16x16x32_bf16 v[32:35], v[176:179], v[192:195], v[32:35]
	v_mfma_f32_16x16x32_bf16 v[20:23], v[168:171], v[222:225], v[20:23]
	v_mfma_f32_16x16x32_bf16 v[16:19], v[176:179], v[222:225], v[16:19]
	v_mfma_f32_16x16x32_bf16 v[4:7], v[168:171], v[230:233], v[4:7]
	v_mfma_f32_16x16x32_bf16 v[0:3], v[176:179], v[230:233], v[0:3]
	v_mfma_f32_16x16x32_bf16 v[52:55], v[172:175], v[188:191], v[52:55]
	v_mfma_f32_16x16x32_bf16 v[48:51], v[180:183], v[188:191], v[48:51]
	v_mfma_f32_16x16x32_bf16 v[36:39], v[172:175], v[196:199], v[36:39]
	v_mfma_f32_16x16x32_bf16 v[32:35], v[180:183], v[196:199], v[32:35]
	v_mfma_f32_16x16x32_bf16 v[20:23], v[172:175], v[226:229], v[20:23]
	v_mfma_f32_16x16x32_bf16 v[16:19], v[180:183], v[226:229], v[16:19]
	v_mfma_f32_16x16x32_bf16 v[4:7], v[172:175], v[234:237], v[4:7]
	v_mfma_f32_16x16x32_bf16 v[0:3], v[180:183], v[234:237], v[0:3]
	s_setprio 0
	s_barrier
; #define PG8_STAGE(bufoff, gbase, voff) do { _Pragma("unroll") for (int _i = 0; _i < 2; ++_i) \
;         __builtin_amdgcn_global_load_lds((const unsigned*)((const char*)(gbase) + (voff)[_i]), (PG8_LAS unsigned*)(lds + (bufoff) + ldsw + _i * 8192), 16, 0, 0); } while (0)
; #define PG8_LDA(dst, b, h) do { _Pragma("unroll") for (int m = 0; m < 4; ++m) _Pragma("unroll") for (int k = 0; k < 2; ++k) dst[m][k] = *(const PG8_LAS bf16x8*)(lds + PG8_SA(b, h) + aoff + m * 2048 + k * 1024); } while (0)
; #define PG8_LDB(dst, b, h) do { _Pragma("unroll") for (int n = 0; n < 2; ++n) _Pragma("unroll") for (int k = 0; k < 2; ++k) dst[n][k] = *(const PG8_LAS bf16x8*)(lds + PG8_SB(b, h) + boff + n * 2048 + k * 1024); } while (0)
; #define PG8_MMA(ai, bj, At, Bt) do { __builtin_amdgcn_s_setprio(1); _Pragma("unroll") for (int m = 0; m < 4; ++m) _Pragma("unroll") for (int n = 0; n < 2; ++n) _Pragma("unroll") for (int k = 0; k < 2; ++k) \
;         acc[ai][bj][m][n] = __builtin_amdgcn_mfma_f32_16x16x32_bf16(Bt[n][k], At[m][k], acc[ai][bj][m][n], 0, 0, 0); __builtin_amdgcn_s_setprio(0); } while (0)
; #define PG8_WAIT_V(n) asm volatile("s_waitcnt vmcnt(" #n ")" ::: "memory")
; #define PG8_WAIT_L(n) asm volatile("s_waitcnt lgkmcnt(" #n ")" ::: "memory")
; #define PG8_BAR __builtin_amdgcn_s_barrier()
; #define PG8_SCHED __builtin_amdgcn_sched_barrier(0)
; template <class Epi, class Sched, bool ALIGN_EPI = false, bool SP2 = false>
; __device__ __forceinline__ void gemm_phase(PG8_LAS unsigned char* lds, const Gemm g, const Sched& S, const Epi& E) {
;     ...
;             PG8_LDB(B0, 1, 0); PG8_LDB(B1, 1, 1); PG8_SCHED; PG8_LDA(At, 1, 0); PG8_STAGE(PG8_SA(0, 1), a2 + hstep, voffA);
;             PG8_WAIT_V(8); PG8_WAIT_L(0); PG8_BAR; PG8_MMA(0, 0, At, B0); PG8_MMA(0, 1, At, B1); PG8_BAR; PG8_SCHED;
;             PG8_LDA(At, 1, 1); PG8_STAGE(PG8_SB(1, 0), b3, voffB); PG8_STAGE(PG8_SB(1, 1), b3 + hstep, voffB); PG8_STAGE(PG8_SA(1, 0), a3, voffA);
;             PG8_WAIT_V(8); PG8_WAIT_L(0); PG8_BAR; PG8_MMA(1, 0, At, B0); PG8_MMA(1, 1, At, B1); PG8_BAR; PG8_SCHED;
	s_add_i32 s88, 0, 0x18000
	v_add_u32_e32 v160, s88, v147
	s_add_i32 s89, 0, 0x1c000
	ds_read_b128 v[140:143], v160
	ds_read_b128 v[150:153], v160 offset:1024
	ds_read_b128 v[154:157], v160 offset:2048
	ds_read_b128 v[164:167], v160 offset:3072
	v_add_u32_e32 v160, s89, v147
	ds_read_b128 v[168:171], v160
	ds_read_b128 v[172:175], v160 offset:1024
	ds_read_b128 v[176:179], v160 offset:2048
	ds_read_b128 v[180:183], v160 offset:3072
	s_add_u32 s52, s52, 0x40000
	s_addc_u32 s53, s53, 0
	s_mov_b32 m0, s75
	ds_read_b128 v[184:187], v149 offset:32768
	ds_read_b128 v[188:191], v149 offset:33792
	ds_read_b128 v[192:195], v149 offset:34816
	ds_read_b128 v[196:199], v149 offset:35840
	ds_read_b128 v[222:225], v149 offset:36864
	ds_read_b128 v[226:229], v149 offset:37888
	ds_read_b128 v[230:233], v149 offset:38912
	ds_read_b128 v[234:237], v149 offset:39936
	global_load_lds_dwordx4 v128, s[52:53]
	s_mov_b32 m0, s81
	s_nop 0
	global_load_lds_dwordx4 v132, s[52:53]
	s_waitcnt vmcnt(8)
	s_waitcnt lgkmcnt(0)
	s_barrier
	s_setprio 1
	s_waitcnt lgkmcnt(0)
	v_mfma_f32_16x16x32_bf16 v[124:127], v[140:143], v[184:187], v[124:127]
	v_mfma_f32_16x16x32_bf16 v[120:123], v[154:157], v[184:187], v[120:123]
	v_mfma_f32_16x16x32_bf16 v[108:111], v[140:143], v[192:195], v[108:111]
	v_mfma_f32_16x16x32_bf16 v[104:107], v[154:157], v[192:195], v[104:107]
	v_mfma_f32_16x16x32_bf16 v[92:95], v[140:143], v[222:225], v[92:95]
	v_mfma_f32_16x16x32_bf16 v[88:91], v[154:157], v[222:225], v[88:91]
	v_mfma_f32_16x16x32_bf16 v[76:79], v[140:143], v[230:233], v[76:79]
	v_mfma_f32_16x16x32_bf16 v[72:75], v[154:157], v[230:233], v[72:75]
	v_mfma_f32_16x16x32_bf16 v[124:127], v[150:153], v[188:191], v[124:127]
	v_mfma_f32_16x16x32_bf16 v[120:123], v[164:167], v[188:191], v[120:123]
	v_mfma_f32_16x16x32_bf16 v[108:111], v[150:153], v[196:199], v[108:111]
	v_mfma_f32_16x16x32_bf16 v[104:107], v[164:167], v[196:199], v[104:107]
	v_mfma_f32_16x16x32_bf16 v[92:95], v[150:153], v[226:229], v[92:95]
	v_mfma_f32_16x16x32_bf16 v[88:91], v[164:167], v[226:229], v[88:91]
	v_mfma_f32_16x16x32_bf16 v[76:79], v[150:153], v[234:237], v[76:79]
	v_mfma_f32_16x16x32_bf16 v[72:75], v[164:167], v[234:237], v[72:75]
	s_setprio 0
	s_setprio 1
	v_mfma_f32_16x16x32_bf16 v[116:119], v[168:171], v[184:187], v[116:119]
	v_mfma_f32_16x16x32_bf16 v[112:115], v[176:179], v[184:187], v[112:115]
	v_mfma_f32_16x16x32_bf16 v[100:103], v[168:171], v[192:195], v[100:103]
	v_mfma_f32_16x16x32_bf16 v[96:99], v[176:179], v[192:195], v[96:99]
	v_mfma_f32_16x16x32_bf16 v[84:87], v[168:171], v[222:225], v[84:87]
	v_mfma_f32_16x16x32_bf16 v[80:83], v[176:179], v[222:225], v[80:83]
	v_mfma_f32_16x16x32_bf16 v[68:71], v[168:171], v[230:233], v[68:71]
	v_mfma_f32_16x16x32_bf16 v[64:67], v[176:179], v[230:233], v[64:67]
	v_mfma_f32_16x16x32_bf16 v[116:119], v[172:175], v[188:191], v[116:119]
	v_mfma_f32_16x16x32_bf16 v[112:115], v[180:183], v[188:191], v[112:115]
	v_mfma_f32_16x16x32_bf16 v[100:103], v[172:175], v[196:199], v[100:103]
	v_mfma_f32_16x16x32_bf16 v[96:99], v[180:183], v[196:199], v[96:99]
	v_mfma_f32_16x16x32_bf16 v[84:87], v[172:175], v[226:229], v[84:87]
	v_mfma_f32_16x16x32_bf16 v[80:83], v[180:183], v[226:229], v[80:83]
	v_mfma_f32_16x16x32_bf16 v[68:71], v[172:175], v[234:237], v[68:71]
	v_mfma_f32_16x16x32_bf16 v[64:67], v[180:183], v[234:237], v[64:67]
	s_setprio 0
	s_barrier
	s_add_i32 s52, s88, s59
	s_mov_b32 m0, s52
	ds_read_b128 v[184:187], v149 offset:49152
	ds_read_b128 v[188:191], v149 offset:50176
	ds_read_b128 v[192:195], v149 offset:51200
	ds_read_b128 v[196:199], v149 offset:52224
	ds_read_b128 v[222:225], v149 offset:53248
	ds_read_b128 v[226:229], v149 offset:54272
	ds_read_b128 v[230:233], v149 offset:55296
	ds_read_b128 v[234:237], v149 offset:56320
	s_add_u32 s4, s4, 0x80
	s_addc_u32 s5, s5, 0
	global_load_lds_dwordx4 v130, s[4:5]
	s_add_i32 m0, s52, 0x2000
	s_add_i32 s52, s89, s59
	global_load_lds_dwordx4 v134, s[4:5]
	s_add_u32 s4, s4, 0x40000
	s_addc_u32 s5, s5, 0
	s_mov_b32 m0, s52
	s_nop 0
	global_load_lds_dwordx4 v130, s[4:5]
	s_add_i32 m0, s52, 0x2000
	s_nop 0
	global_load_lds_dwordx4 v134, s[4:5]
	s_mov_b32 m0, s84
	s_nop 0
	global_load_lds_dwordx4 v128, s[98:99]
	s_mov_b32 m0, s85
	s_nop 0
	global_load_lds_dwordx4 v132, s[98:99]
	s_waitcnt vmcnt(8)
	s_waitcnt lgkmcnt(0)
	s_barrier
	s_setprio 1
	s_waitcnt lgkmcnt(0)
	v_mfma_f32_16x16x32_bf16 v[60:63], v[140:143], v[184:187], v[60:63]
	v_mfma_f32_16x16x32_bf16 v[56:59], v[154:157], v[184:187], v[56:59]
	v_mfma_f32_16x16x32_bf16 v[44:47], v[140:143], v[192:195], v[44:47]
	v_mfma_f32_16x16x32_bf16 v[40:43], v[154:157], v[192:195], v[40:43]
	v_mfma_f32_16x16x32_bf16 v[28:31], v[140:143], v[222:225], v[28:31]
	v_mfma_f32_16x16x32_bf16 v[24:27], v[154:157], v[222:225], v[24:27]
	v_mfma_f32_16x16x32_bf16 v[12:15], v[140:143], v[230:233], v[12:15]
	v_mfma_f32_16x16x32_bf16 v[8:11], v[154:157], v[230:233], v[8:11]
	v_mfma_f32_16x16x32_bf16 v[60:63], v[150:153], v[188:191], v[60:63]
	v_mfma_f32_16x16x32_bf16 v[56:59], v[164:167], v[188:191], v[56:59]
	v_mfma_f32_16x16x32_bf16 v[44:47], v[150:153], v[196:199], v[44:47]
	v_mfma_f32_16x16x32_bf16 v[40:43], v[164:167], v[196:199], v[40:43]
	v_mfma_f32_16x16x32_bf16 v[28:31], v[150:153], v[226:229], v[28:31]
	v_mfma_f32_16x16x32_bf16 v[24:27], v[164:167], v[226:229], v[24:27]
	v_mfma_f32_16x16x32_bf16 v[12:15], v[150:153], v[234:237], v[12:15]
	v_mfma_f32_16x16x32_bf16 v[8:11], v[164:167], v[234:237], v[8:11]
	s_setprio 0
	s_setprio 1
	v_mfma_f32_16x16x32_bf16 v[52:55], v[168:171], v[184:187], v[52:55]
	v_mfma_f32_16x16x32_bf16 v[48:51], v[176:179], v[184:187], v[48:51]
	v_mfma_f32_16x16x32_bf16 v[36:39], v[168:171], v[192:195], v[36:39]
	v_mfma_f32_16x16x32_bf16 v[32:35], v[176:179], v[192:195], v[32:35]
	v_mfma_f32_16x16x32_bf16 v[20:23], v[168:171], v[222:225], v[20:23]
	v_mfma_f32_16x16x32_bf16 v[16:19], v[176:179], v[222:225], v[16:19]
	v_mfma_f32_16x16x32_bf16 v[4:7], v[168:171], v[230:233], v[4:7]
	v_mfma_f32_16x16x32_bf16 v[0:3], v[176:179], v[230:233], v[0:3]
	v_mfma_f32_16x16x32_bf16 v[52:55], v[172:175], v[188:191], v[52:55]
	v_mfma_f32_16x16x32_bf16 v[48:51], v[180:183], v[188:191], v[48:51]
	v_mfma_f32_16x16x32_bf16 v[36:39], v[172:175], v[196:199], v[36:39]
	v_mfma_f32_16x16x32_bf16 v[32:35], v[180:183], v[196:199], v[32:35]
	v_mfma_f32_16x16x32_bf16 v[20:23], v[172:175], v[226:229], v[20:23]
	v_mfma_f32_16x16x32_bf16 v[16:19], v[180:183], v[226:229], v[16:19]
	v_mfma_f32_16x16x32_bf16 v[4:7], v[172:175], v[234:237], v[4:7]
	v_mfma_f32_16x16x32_bf16 v[0:3], v[180:183], v[234:237], v[0:3]
	s_setprio 0
	s_barrier
	s_add_i32 s87, s87, 2
	s_add_u32 s82, s82, 0x100
	s_addc_u32 s83, s83, 0
	s_add_u32 s29, s29, 0x100
	s_addc_u32 s43, s43, 0
	s_cmp_gt_u32 s87, 13
	s_cbranch_scc0 .LBB0_86
	s_and_b64 vcc, exec, s[12:13]
	s_cbranch_vccz .LBB0_89
	s_barrier

; #define PG8_STAGE(bufoff, gbase, voff) do { _Pragma("unroll") for (int _i = 0; _i < 2; ++_i) \
;         __builtin_amdgcn_global_load_lds((const unsigned*)((const char*)(gbase) + (voff)[_i]), (PG8_LAS unsigned*)(lds + (bufoff) + ldsw + _i * 8192), 16, 0, 0); } while (0)
; #define PG8_LDA(dst, b, h) do { _Pragma("unroll") for (int m = 0; m < 4; ++m) _Pragma("unroll") for (int k = 0; k < 2; ++k) dst[m][k] = *(const PG8_LAS bf16x8*)(lds + PG8_SA(b, h) + aoff + m * 2048 + k * 1024); } while (0)
; #define PG8_LDB(dst, b, h) do { _Pragma("unroll") for (int n = 0; n < 2; ++n) _Pragma("unroll") for (int k = 0; k < 2; ++k) dst[n][k] = *(const PG8_LAS bf16x8*)(lds + PG8_SB(b, h) + boff + n * 2048 + k * 1024); } while (0)
; #define PG8_MMA(ai, bj, At, Bt) do { __builtin_amdgcn_s_setprio(1); _Pragma("unroll") for (int m = 0; m < 4; ++m) _Pragma("unroll") for (int n = 0; n < 2; ++n) _Pragma("unroll") for (int k = 0; k < 2; ++k) \
;         acc[ai][bj][m][n] = __builtin_amdgcn_mfma_f32_16x16x32_bf16(Bt[n][k], At[m][k], acc[ai][bj][m][n], 0, 0, 0); __builtin_amdgcn_s_setprio(0); } while (0)
; #define PG8_WAIT_V(n) asm volatile("s_waitcnt vmcnt(" #n ")" ::: "memory")
; #define PG8_WAIT_L(n) asm volatile("s_waitcnt lgkmcnt(" #n ")" ::: "memory")
; template <class Epi, class Sched, bool ALIGN_EPI = false, bool SP2 = false>
; __device__ __forceinline__ void gemm_phase(PG8_LAS unsigned char* lds, const Gemm g, const Sched& S, const Epi& E) {
;     ...
;             const bool last = (t == nt - 2);
;             const char* a1 = cA + (size_t)(t + 1) * kstep;
;             const char* a2 = last ? nA : cA + (size_t)(t + 2) * kstep; const char* b2 = last ? nB : cB + (size_t)(t + 2) * kstep;
;             const char* a3 = a2 + kstep; const char* b3 = b2 + kstep;
;             if (last && has_next) S.a_ready(nxt);
;             if constexpr (SP2) {
;             PG8_LDB(B0, 0, 0); PG8_LDB(B1, 0, 1); PG8_SCHED; PG8_LDA(At, 0, 0); PG8_STAGE(PG8_SA(1, 1), a1 + hstep, voffA);
;             PG8_WAIT_V(8); PG8_WAIT_L(0); PG8_BAR; PG8_MMA(0, 0, At, B0); PG8_MMA(0, 1, At, B1); PG8_BAR; PG8_SCHED;
;             PG8_LDA(At, 0, 1); PG8_STAGE(PG8_SB(0, 0), b2, voffB); PG8_STAGE(PG8_SB(0, 1), b2 + hstep, voffB); PG8_STAGE(PG8_SA(0, 0), a2, voffA);
;             PG8_WAIT_V(8); PG8_WAIT_L(0); PG8_BAR; PG8_MMA(1, 0, At, B0); PG8_MMA(1, 1, At, B1); PG8_BAR; PG8_SCHED;
.LBB0_322:
	s_add_i32 s56, 0, 0x10000
	v_add_u32_e32 v158, s56, v139
	s_add_i32 vcc_lo, 0, 0x14000
	s_waitcnt lgkmcnt(0)
	ds_read_b128 v[154:157], v158
	ds_read_b128 v[164:167], v158 offset:1024
	ds_read_b128 v[168:171], v158 offset:2048
	ds_read_b128 v[172:175], v158 offset:3072
	v_add_u32_e32 v158, vcc_lo, v139
	ds_read_b128 v[176:179], v158
	ds_read_b128 v[180:183], v158 offset:1024
	ds_read_b128 v[184:187], v158 offset:2048
	ds_read_b128 v[188:191], v158 offset:3072
	s_add_i32 m0, s89, 0xc000
	ds_read_b128 v[192:195], v145
	ds_read_b128 v[196:199], v145 offset:1024
	ds_read_b128 v[222:225], v145 offset:2048
	ds_read_b128 v[226:229], v145 offset:3072
	ds_read_b128 v[230:233], v145 offset:4096
	ds_read_b128 v[234:237], v145 offset:5120
	ds_read_b128 v[238:241], v145 offset:6144
	ds_read_b128 v[242:245], v145 offset:7168
	global_load_lds_dwordx4 v150, s[14:15]
	s_add_i32 m0, s89, 0xe000
	s_nop 0
	global_load_lds_dwordx4 v152, s[14:15]
	s_add_u32 s4, s14, 0xfff80080
	s_addc_u32 s5, s15, -1
	s_cmp_eq_u32 s55, 28
	s_cselect_b32 s53, s1, s5
	s_cselect_b32 s52, s28, s4
	s_cselect_b32 s5, s29, s54
	s_cselect_b32 s4, s43, s45
	s_waitcnt vmcnt(8)
	s_waitcnt lgkmcnt(0)
	s_barrier
	s_setprio 1
	s_waitcnt lgkmcnt(0)
	v_mfma_f32_16x16x32_bf16 v[124:127], v[154:157], v[192:195], v[124:127]
	v_mfma_f32_16x16x32_bf16 v[120:123], v[168:171], v[192:195], v[120:123]
	v_mfma_f32_16x16x32_bf16 v[116:119], v[154:157], v[222:225], v[116:119]
	v_mfma_f32_16x16x32_bf16 v[112:115], v[168:171], v[222:225], v[112:115]
	v_mfma_f32_16x16x32_bf16 v[108:111], v[154:157], v[230:233], v[108:111]
	v_mfma_f32_16x16x32_bf16 v[104:107], v[168:171], v[230:233], v[104:107]
	v_mfma_f32_16x16x32_bf16 v[100:103], v[154:157], v[238:241], v[100:103]
	v_mfma_f32_16x16x32_bf16 v[96:99], v[168:171], v[238:241], v[96:99]
	v_mfma_f32_16x16x32_bf16 v[124:127], v[164:167], v[196:199], v[124:127]
	v_mfma_f32_16x16x32_bf16 v[120:123], v[172:175], v[196:199], v[120:123]
	v_mfma_f32_16x16x32_bf16 v[116:119], v[164:167], v[226:229], v[116:119]
	v_mfma_f32_16x16x32_bf16 v[112:115], v[172:175], v[226:229], v[112:115]
	v_mfma_f32_16x16x32_bf16 v[108:111], v[164:167], v[234:237], v[108:111]
	v_mfma_f32_16x16x32_bf16 v[104:107], v[172:175], v[234:237], v[104:107]
	v_mfma_f32_16x16x32_bf16 v[100:103], v[164:167], v[242:245], v[100:103]
	v_mfma_f32_16x16x32_bf16 v[96:99], v[172:175], v[242:245], v[96:99]
	s_setprio 0
	s_setprio 1
	v_mfma_f32_16x16x32_bf16 v[92:95], v[176:179], v[192:195], v[92:95]
	v_mfma_f32_16x16x32_bf16 v[88:91], v[184:187], v[192:195], v[88:91]
	v_mfma_f32_16x16x32_bf16 v[84:87], v[176:179], v[222:225], v[84:87]
	v_mfma_f32_16x16x32_bf16 v[80:83], v[184:187], v[222:225], v[80:83]
	v_mfma_f32_16x16x32_bf16 v[76:79], v[176:179], v[230:233], v[76:79]
	v_mfma_f32_16x16x32_bf16 v[72:75], v[184:187], v[230:233], v[72:75]
	v_mfma_f32_16x16x32_bf16 v[68:71], v[176:179], v[238:241], v[68:71]
	v_mfma_f32_16x16x32_bf16 v[64:67], v[184:187], v[238:241], v[64:67]
	v_mfma_f32_16x16x32_bf16 v[92:95], v[180:183], v[196:199], v[92:95]
	v_mfma_f32_16x16x32_bf16 v[88:91], v[188:191], v[196:199], v[88:91]
	v_mfma_f32_16x16x32_bf16 v[84:87], v[180:183], v[226:229], v[84:87]
	v_mfma_f32_16x16x32_bf16 v[80:83], v[188:191], v[226:229], v[80:83]
	v_mfma_f32_16x16x32_bf16 v[76:79], v[180:183], v[234:237], v[76:79]
	v_mfma_f32_16x16x32_bf16 v[72:75], v[188:191], v[234:237], v[72:75]
	v_mfma_f32_16x16x32_bf16 v[68:71], v[180:183], v[242:245], v[68:71]
	v_mfma_f32_16x16x32_bf16 v[64:67], v[188:191], v[242:245], v[64:67]
	s_setprio 0
	s_barrier
	s_add_i32 s56, s56, s63
	s_mov_b32 m0, s56
	ds_read_b128 v[192:195], v145 offset:16384
	ds_read_b128 v[196:199], v145 offset:17408
	ds_read_b128 v[222:225], v145 offset:18432
	ds_read_b128 v[226:229], v145 offset:19456
	ds_read_b128 v[230:233], v145 offset:20480
	ds_read_b128 v[234:237], v145 offset:21504
	ds_read_b128 v[238:241], v145 offset:22528
	ds_read_b128 v[242:245], v145 offset:23552
	global_load_lds_dwordx4 v130, s[4:5]
	s_add_i32 m0, s56, 0x2000
	s_add_u32 s56, s4, 0x80000
	s_addc_u32 s57, s5, 0
	s_add_i32 vcc_lo, vcc_lo, s63
	global_load_lds_dwordx4 v134, s[4:5]
	s_mov_b32 m0, vcc_lo
	s_nop 0
	global_load_lds_dwordx4 v130, s[56:57]
	s_add_i32 m0, vcc_lo, 0x2000
	s_nop 0
	global_load_lds_dwordx4 v134, s[56:57]
	s_mov_b32 m0, s89
	s_nop 0
	global_load_lds_dwordx4 v128, s[52:53]
	s_mov_b32 m0, s91
	s_nop 0
	global_load_lds_dwordx4 v132, s[52:53]
	s_add_u32 s98, s52, 0x80
	s_addc_u32 s99, s53, 0
	s_waitcnt vmcnt(8)
	s_waitcnt lgkmcnt(0)
	s_barrier
; #define PG8_STAGE(bufoff, gbase, voff) do { _Pragma("unroll") for (int _i = 0; _i < 2; ++_i) \
;         __builtin_amdgcn_global_load_lds((const unsigned*)((const char*)(gbase) + (voff)[_i]), (PG8_LAS unsigned*)(lds + (bufoff) + ldsw + _i * 8192), 16, 0, 0); } while (0)
; #define PG8_LDA(dst, b, h) do { _Pragma("unroll") for (int m = 0; m < 4; ++m) _Pragma("unroll") for (int k = 0; k < 2; ++k) dst[m][k] = *(const PG8_LAS bf16x8*)(lds + PG8_SA(b, h) + aoff + m * 2048 + k * 1024); } while (0)
; #define PG8_LDB(dst, b, h) do { _Pragma("unroll") for (int n = 0; n < 2; ++n) _Pragma("unroll") for (int k = 0; k < 2; ++k) dst[n][k] = *(const PG8_LAS bf16x8*)(lds + PG8_SB(b, h) + boff + n * 2048 + k * 1024); } while (0)
; #define PG8_MMA(ai, bj, At, Bt) do { __builtin_amdgcn_s_setprio(1); _Pragma("unroll") for (int m = 0; m < 4; ++m) _Pragma("unroll") for (int n = 0; n < 2; ++n) _Pragma("unroll") for (int k = 0; k < 2; ++k) \
;         acc[ai][bj][m][n] = __builtin_amdgcn_mfma_f32_16x16x32_bf16(Bt[n][k], At[m][k], acc[ai][bj][m][n], 0, 0, 0); __builtin_amdgcn_s_setprio(0); } while (0)
; #define PG8_WAIT_V(n) asm volatile("s_waitcnt vmcnt(" #n ")" ::: "memory")
; #define PG8_WAIT_L(n) asm volatile("s_waitcnt lgkmcnt(" #n ")" ::: "memory")
; #define PG8_BAR __builtin_amdgcn_s_barrier()
; #define PG8_SCHED __builtin_amdgcn_sched_barrier(0)
; template <class Epi, class Sched, bool ALIGN_EPI = false, bool SP2 = false>
; __device__ __forceinline__ void gemm_phase(PG8_LAS unsigned char* lds, const Gemm g, const Sched& S, const Epi& E) {
;     ...
;             PG8_WAIT_V(8); PG8_WAIT_L(0); PG8_BAR; PG8_MMA(1, 0, At, B0); PG8_MMA(1, 1, At, B1); PG8_BAR; PG8_SCHED;
;             PG8_LDB(B0, 1, 0); PG8_LDB(B1, 1, 1); PG8_SCHED; PG8_LDA(At, 1, 0); PG8_STAGE(PG8_SA(0, 1), a2 + hstep, voffA);
;             PG8_WAIT_V(8); PG8_WAIT_L(0); PG8_BAR; PG8_MMA(0, 0, At, B0); PG8_MMA(0, 1, At, B1); PG8_BAR; PG8_SCHED;
	s_setprio 1
	s_waitcnt lgkmcnt(0)
	v_mfma_f32_16x16x32_bf16 v[60:63], v[154:157], v[192:195], v[60:63]
	v_mfma_f32_16x16x32_bf16 v[56:59], v[168:171], v[192:195], v[56:59]
	v_mfma_f32_16x16x32_bf16 v[52:55], v[154:157], v[222:225], v[52:55]
	v_mfma_f32_16x16x32_bf16 v[48:51], v[168:171], v[222:225], v[48:51]
	v_mfma_f32_16x16x32_bf16 v[44:47], v[154:157], v[230:233], v[44:47]
	v_mfma_f32_16x16x32_bf16 v[40:43], v[168:171], v[230:233], v[40:43]
	v_mfma_f32_16x16x32_bf16 v[36:39], v[154:157], v[238:241], v[36:39]
	v_mfma_f32_16x16x32_bf16 v[32:35], v[168:171], v[238:241], v[32:35]
	v_mfma_f32_16x16x32_bf16 v[60:63], v[164:167], v[196:199], v[60:63]
	v_mfma_f32_16x16x32_bf16 v[56:59], v[172:175], v[196:199], v[56:59]
	v_mfma_f32_16x16x32_bf16 v[52:55], v[164:167], v[226:229], v[52:55]
	v_mfma_f32_16x16x32_bf16 v[48:51], v[172:175], v[226:229], v[48:51]
	v_mfma_f32_16x16x32_bf16 v[44:47], v[164:167], v[234:237], v[44:47]
	v_mfma_f32_16x16x32_bf16 v[40:43], v[172:175], v[234:237], v[40:43]
	v_mfma_f32_16x16x32_bf16 v[36:39], v[164:167], v[242:245], v[36:39]
	v_mfma_f32_16x16x32_bf16 v[32:35], v[172:175], v[242:245], v[32:35]
	s_setprio 0
	s_setprio 1
	v_mfma_f32_16x16x32_bf16 v[28:31], v[176:179], v[192:195], v[28:31]
	v_mfma_f32_16x16x32_bf16 v[24:27], v[184:187], v[192:195], v[24:27]
	v_mfma_f32_16x16x32_bf16 v[20:23], v[176:179], v[222:225], v[20:23]
	v_mfma_f32_16x16x32_bf16 v[16:19], v[184:187], v[222:225], v[16:19]
	v_mfma_f32_16x16x32_bf16 v[12:15], v[176:179], v[230:233], v[12:15]
	v_mfma_f32_16x16x32_bf16 v[8:11], v[184:187], v[230:233], v[8:11]
	v_mfma_f32_16x16x32_bf16 v[4:7], v[176:179], v[238:241], v[4:7]
	v_mfma_f32_16x16x32_bf16 v[0:3], v[184:187], v[238:241], v[0:3]
	v_mfma_f32_16x16x32_bf16 v[28:31], v[180:183], v[196:199], v[28:31]
	v_mfma_f32_16x16x32_bf16 v[24:27], v[188:191], v[196:199], v[24:27]
	v_mfma_f32_16x16x32_bf16 v[20:23], v[180:183], v[226:229], v[20:23]
	v_mfma_f32_16x16x32_bf16 v[16:19], v[188:191], v[226:229], v[16:19]
	v_mfma_f32_16x16x32_bf16 v[12:15], v[180:183], v[234:237], v[12:15]
	v_mfma_f32_16x16x32_bf16 v[8:11], v[188:191], v[234:237], v[8:11]
	v_mfma_f32_16x16x32_bf16 v[4:7], v[180:183], v[242:245], v[4:7]
	v_mfma_f32_16x16x32_bf16 v[0:3], v[188:191], v[242:245], v[0:3]
	s_setprio 0
	s_barrier
	s_add_i32 s56, 0, 0x18000
	v_add_u32_e32 v160, s56, v139
	s_add_i32 s57, 0, 0x1c000
	ds_read_b128 v[154:157], v160
	ds_read_b128 v[164:167], v160 offset:1024
	ds_read_b128 v[168:171], v160 offset:2048
	ds_read_b128 v[172:175], v160 offset:3072
	v_add_u32_e32 v160, s57, v139
	ds_read_b128 v[176:179], v160
	ds_read_b128 v[180:183], v160 offset:1024
	ds_read_b128 v[184:187], v160 offset:2048
	ds_read_b128 v[188:191], v160 offset:3072
	s_add_u32 s52, s52, 0x80000
	s_addc_u32 s53, s53, 0
	s_mov_b32 m0, s12
	ds_read_b128 v[192:195], v145 offset:32768
	ds_read_b128 v[196:199], v145 offset:33792
	ds_read_b128 v[222:225], v145 offset:34816
	ds_read_b128 v[226:229], v145 offset:35840
	ds_read_b128 v[230:233], v145 offset:36864
	ds_read_b128 v[234:237], v145 offset:37888
	ds_read_b128 v[238:241], v145 offset:38912
	ds_read_b128 v[242:245], v145 offset:39936
	global_load_lds_dwordx4 v128, s[52:53]
	s_mov_b32 m0, s13
	s_nop 0
	global_load_lds_dwordx4 v132, s[52:53]
	s_waitcnt vmcnt(8)
	s_waitcnt lgkmcnt(0)
	s_barrier
	s_setprio 1
	s_waitcnt lgkmcnt(0)
	v_mfma_f32_16x16x32_bf16 v[124:127], v[154:157], v[192:195], v[124:127]
	v_mfma_f32_16x16x32_bf16 v[120:123], v[168:171], v[192:195], v[120:123]
	v_mfma_f32_16x16x32_bf16 v[116:119], v[154:157], v[222:225], v[116:119]
	v_mfma_f32_16x16x32_bf16 v[112:115], v[168:171], v[222:225], v[112:115]
	v_mfma_f32_16x16x32_bf16 v[108:111], v[154:157], v[230:233], v[108:111]
	v_mfma_f32_16x16x32_bf16 v[104:107], v[168:171], v[230:233], v[104:107]
	v_mfma_f32_16x16x32_bf16 v[100:103], v[154:157], v[238:241], v[100:103]
	v_mfma_f32_16x16x32_bf16 v[96:99], v[168:171], v[238:241], v[96:99]
	v_mfma_f32_16x16x32_bf16 v[124:127], v[164:167], v[196:199], v[124:127]
	v_mfma_f32_16x16x32_bf16 v[120:123], v[172:175], v[196:199], v[120:123]
	v_mfma_f32_16x16x32_bf16 v[116:119], v[164:167], v[226:229], v[116:119]
	v_mfma_f32_16x16x32_bf16 v[112:115], v[172:175], v[226:229], v[112:115]
	v_mfma_f32_16x16x32_bf16 v[108:111], v[164:167], v[234:237], v[108:111]
	v_mfma_f32_16x16x32_bf16 v[104:107], v[172:175], v[234:237], v[104:107]
	v_mfma_f32_16x16x32_bf16 v[100:103], v[164:167], v[242:245], v[100:103]
	v_mfma_f32_16x16x32_bf16 v[96:99], v[172:175], v[242:245], v[96:99]
	s_setprio 0
	s_setprio 1
	v_mfma_f32_16x16x32_bf16 v[92:95], v[176:179], v[192:195], v[92:95]
	v_mfma_f32_16x16x32_bf16 v[88:91], v[184:187], v[192:195], v[88:91]
	v_mfma_f32_16x16x32_bf16 v[84:87], v[176:179], v[222:225], v[84:87]
	v_mfma_f32_16x16x32_bf16 v[80:83], v[184:187], v[222:225], v[80:83]
	v_mfma_f32_16x16x32_bf16 v[76:79], v[176:179], v[230:233], v[76:79]
	v_mfma_f32_16x16x32_bf16 v[72:75], v[184:187], v[230:233], v[72:75]
	v_mfma_f32_16x16x32_bf16 v[68:71], v[176:179], v[238:241], v[68:71]
	v_mfma_f32_16x16x32_bf16 v[64:67], v[184:187], v[238:241], v[64:67]
	v_mfma_f32_16x16x32_bf16 v[92:95], v[180:183], v[196:199], v[92:95]
	v_mfma_f32_16x16x32_bf16 v[88:91], v[188:191], v[196:199], v[88:91]
	v_mfma_f32_16x16x32_bf16 v[84:87], v[180:183], v[226:229], v[84:87]
	v_mfma_f32_16x16x32_bf16 v[80:83], v[188:191], v[226:229], v[80:83]
	v_mfma_f32_16x16x32_bf16 v[76:79], v[180:183], v[234:237], v[76:79]
	v_mfma_f32_16x16x32_bf16 v[72:75], v[188:191], v[234:237], v[72:75]
	v_mfma_f32_16x16x32_bf16 v[68:71], v[180:183], v[242:245], v[68:71]
	v_mfma_f32_16x16x32_bf16 v[64:67], v[188:191], v[242:245], v[64:67]
	s_setprio 0
	s_barrier
; #define PG8_STAGE(bufoff, gbase, voff) do { _Pragma("unroll") for (int _i = 0; _i < 2; ++_i) \
;         __builtin_amdgcn_global_load_lds((const unsigned*)((const char*)(gbase) + (voff)[_i]), (PG8_LAS unsigned*)(lds + (bufoff) + ldsw + _i * 8192), 16, 0, 0); } while (0)
; #define PG8_LDA(dst, b, h) do { _Pragma("unroll") for (int m = 0; m < 4; ++m) _Pragma("unroll") for (int k = 0; k < 2; ++k) dst[m][k] = *(const PG8_LAS bf16x8*)(lds + PG8_SA(b, h) + aoff + m * 2048 + k * 1024); } while (0)
; #define PG8_MMA(ai, bj, At, Bt) do { __builtin_amdgcn_s_setprio(1); _Pragma("unroll") for (int m = 0; m < 4; ++m) _Pragma("unroll") for (int n = 0; n < 2; ++n) _Pragma("unroll") for (int k = 0; k < 2; ++k) \
;         acc[ai][bj][m][n] = __builtin_amdgcn_mfma_f32_16x16x32_bf16(Bt[n][k], At[m][k], acc[ai][bj][m][n], 0, 0, 0); __builtin_amdgcn_s_setprio(0); } while (0)
; #define PG8_WAIT_V(n) asm volatile("s_waitcnt vmcnt(" #n ")" ::: "memory")
; #define PG8_WAIT_L(n) asm volatile("s_waitcnt lgkmcnt(" #n ")" ::: "memory")
; #define PG8_BAR __builtin_amdgcn_s_barrier()
; #define PG8_SCHED __builtin_amdgcn_sched_barrier(0)
; template <class Epi, class Sched, bool ALIGN_EPI = false, bool SP2 = false>
; __device__ __forceinline__ void gemm_phase(PG8_LAS unsigned char* lds, const Gemm g, const Sched& S, const Epi& E) {
;     ...
;             PG8_LDA(At, 1, 1); PG8_STAGE(PG8_SB(1, 0), b3, voffB); PG8_STAGE(PG8_SB(1, 1), b3 + hstep, voffB); PG8_STAGE(PG8_SA(1, 0), a3, voffA);
;             PG8_WAIT_V(8); PG8_WAIT_L(0); PG8_BAR; PG8_MMA(1, 0, At, B0); PG8_MMA(1, 1, At, B1); PG8_BAR; PG8_SCHED;
	s_add_i32 s52, s56, s63
	s_mov_b32 m0, s52
	ds_read_b128 v[192:195], v145 offset:49152
	ds_read_b128 v[196:199], v145 offset:50176
	ds_read_b128 v[222:225], v145 offset:51200
	ds_read_b128 v[226:229], v145 offset:52224
	ds_read_b128 v[230:233], v145 offset:53248
	ds_read_b128 v[234:237], v145 offset:54272
	ds_read_b128 v[238:241], v145 offset:55296
	ds_read_b128 v[242:245], v145 offset:56320
	s_add_u32 s4, s4, 0x80
	s_addc_u32 s5, s5, 0
	global_load_lds_dwordx4 v130, s[4:5]
	s_add_i32 m0, s52, 0x2000
	s_add_i32 s52, s57, s63
	global_load_lds_dwordx4 v134, s[4:5]
	s_add_u32 s4, s4, 0x80000
	s_addc_u32 s5, s5, 0
	s_mov_b32 m0, s52
	s_nop 0
	global_load_lds_dwordx4 v130, s[4:5]
	s_add_i32 m0, s52, 0x2000
	s_nop 0
	global_load_lds_dwordx4 v134, s[4:5]
	s_mov_b32 m0, s78
	s_nop 0
	global_load_lds_dwordx4 v128, s[98:99]
	s_mov_b32 m0, s79
	s_nop 0
	global_load_lds_dwordx4 v132, s[98:99]
	s_waitcnt vmcnt(8)
	s_waitcnt lgkmcnt(0)
	s_barrier
	s_setprio 1
	s_waitcnt lgkmcnt(0)
	v_mfma_f32_16x16x32_bf16 v[60:63], v[154:157], v[192:195], v[60:63]
	v_mfma_f32_16x16x32_bf16 v[56:59], v[168:171], v[192:195], v[56:59]
	v_mfma_f32_16x16x32_bf16 v[52:55], v[154:157], v[222:225], v[52:55]
	v_mfma_f32_16x16x32_bf16 v[48:51], v[168:171], v[222:225], v[48:51]
	v_mfma_f32_16x16x32_bf16 v[44:47], v[154:157], v[230:233], v[44:47]
	v_mfma_f32_16x16x32_bf16 v[40:43], v[168:171], v[230:233], v[40:43]
	v_mfma_f32_16x16x32_bf16 v[36:39], v[154:157], v[238:241], v[36:39]
	v_mfma_f32_16x16x32_bf16 v[32:35], v[168:171], v[238:241], v[32:35]
	v_mfma_f32_16x16x32_bf16 v[60:63], v[164:167], v[196:199], v[60:63]
	v_mfma_f32_16x16x32_bf16 v[56:59], v[172:175], v[196:199], v[56:59]
	v_mfma_f32_16x16x32_bf16 v[52:55], v[164:167], v[226:229], v[52:55]
	v_mfma_f32_16x16x32_bf16 v[48:51], v[172:175], v[226:229], v[48:51]
	v_mfma_f32_16x16x32_bf16 v[44:47], v[164:167], v[234:237], v[44:47]
	v_mfma_f32_16x16x32_bf16 v[40:43], v[172:175], v[234:237], v[40:43]
	v_mfma_f32_16x16x32_bf16 v[36:39], v[164:167], v[242:245], v[36:39]
	v_mfma_f32_16x16x32_bf16 v[32:35], v[172:175], v[242:245], v[32:35]
	s_setprio 0
	s_setprio 1
	v_mfma_f32_16x16x32_bf16 v[28:31], v[176:179], v[192:195], v[28:31]
	v_mfma_f32_16x16x32_bf16 v[24:27], v[184:187], v[192:195], v[24:27]
	v_mfma_f32_16x16x32_bf16 v[20:23], v[176:179], v[222:225], v[20:23]
	v_mfma_f32_16x16x32_bf16 v[16:19], v[184:187], v[222:225], v[16:19]
	v_mfma_f32_16x16x32_bf16 v[12:15], v[176:179], v[230:233], v[12:15]
	v_mfma_f32_16x16x32_bf16 v[8:11], v[184:187], v[230:233], v[8:11]
	v_mfma_f32_16x16x32_bf16 v[4:7], v[176:179], v[238:241], v[4:7]
	v_mfma_f32_16x16x32_bf16 v[0:3], v[184:187], v[238:241], v[0:3]
	v_mfma_f32_16x16x32_bf16 v[28:31], v[180:183], v[196:199], v[28:31]
	v_mfma_f32_16x16x32_bf16 v[24:27], v[188:191], v[196:199], v[24:27]
	v_mfma_f32_16x16x32_bf16 v[20:23], v[180:183], v[226:229], v[20:23]
	v_mfma_f32_16x16x32_bf16 v[16:19], v[188:191], v[226:229], v[16:19]
	v_mfma_f32_16x16x32_bf16 v[12:15], v[180:183], v[234:237], v[12:15]
	v_mfma_f32_16x16x32_bf16 v[8:11], v[188:191], v[234:237], v[8:11]
	v_mfma_f32_16x16x32_bf16 v[4:7], v[180:183], v[242:245], v[4:7]
	v_mfma_f32_16x16x32_bf16 v[0:3], v[188:191], v[242:245], v[0:3]
	s_setprio 0
	s_barrier
	s_add_i32 s55, s55, 2
	s_add_u32 s14, s14, 0x100
	s_addc_u32 s15, s15, 0
	s_add_u32 s45, s45, 0x100
	s_addc_u32 s54, s54, 0
	s_cmp_gt_u32 s55, 29
	s_cbranch_scc0 .LBB0_322
	s_and_b64 vcc, exec, s[82:83]
	s_cbranch_vccz .LBB0_325
	s_barrier

; #define PG8_STAGE(bufoff, gbase, voff) do { _Pragma("unroll") for (int _i = 0; _i < 2; ++_i) \
;         __builtin_amdgcn_global_load_lds((const unsigned*)((const char*)(gbase) + (voff)[_i]), (PG8_LAS unsigned*)(lds + (bufoff) + ldsw + _i * 8192), 16, 0, 0); } while (0)
; #define PG8_LDA(dst, b, h) do { _Pragma("unroll") for (int m = 0; m < 4; ++m) _Pragma("unroll") for (int k = 0; k < 2; ++k) dst[m][k] = *(const PG8_LAS bf16x8*)(lds + PG8_SA(b, h) + aoff + m * 2048 + k * 1024); } while (0)
; #define PG8_LDB(dst, b, h) do { _Pragma("unroll") for (int n = 0; n < 2; ++n) _Pragma("unroll") for (int k = 0; k < 2; ++k) dst[n][k] = *(const PG8_LAS bf16x8*)(lds + PG8_SB(b, h) + boff + n * 2048 + k * 1024); } while (0)
; #define PG8_MMA(ai, bj, At, Bt) do { __builtin_amdgcn_s_setprio(1); _Pragma("unroll") for (int m = 0; m < 4; ++m) _Pragma("unroll") for (int n = 0; n < 2; ++n) _Pragma("unroll") for (int k = 0; k < 2; ++k) \
;         acc[ai][bj][m][n] = __builtin_amdgcn_mfma_f32_16x16x32_bf16(Bt[n][k], At[m][k], acc[ai][bj][m][n], 0, 0, 0); __builtin_amdgcn_s_setprio(0); } while (0)
; #define PG8_WAIT_V(n) asm volatile("s_waitcnt vmcnt(" #n ")" ::: "memory")
; #define PG8_WAIT_L(n) asm volatile("s_waitcnt lgkmcnt(" #n ")" ::: "memory")
; template <class Epi, class Sched, bool ALIGN_EPI = false, bool SP2 = false>
; __device__ __forceinline__ void gemm_phase(PG8_LAS unsigned char* lds, const Gemm g, const Sched& S, const Epi& E) {
;     ...
;             const bool last = (t == nt - 2);
;             const char* a1 = cA + (size_t)(t + 1) * kstep;
;             const char* a2 = last ? nA : cA + (size_t)(t + 2) * kstep; const char* b2 = last ? nB : cB + (size_t)(t + 2) * kstep;
;             const char* a3 = a2 + kstep; const char* b3 = b2 + kstep;
;             if (last && has_next) S.a_ready(nxt);
;             if constexpr (SP2) {
;             PG8_LDB(B0, 0, 0); PG8_LDB(B1, 0, 1); PG8_SCHED; PG8_LDA(At, 0, 0); PG8_STAGE(PG8_SA(1, 1), a1 + hstep, voffA);
;             PG8_WAIT_V(8); PG8_WAIT_L(0); PG8_BAR; PG8_MMA(0, 0, At, B0); PG8_MMA(0, 1, At, B1); PG8_BAR; PG8_SCHED;
;             PG8_LDA(At, 0, 1); PG8_STAGE(PG8_SB(0, 0), b2, voffB); PG8_STAGE(PG8_SB(0, 1), b2 + hstep, voffB); PG8_STAGE(PG8_SA(0, 0), a2, voffA);
;             PG8_WAIT_V(8); PG8_WAIT_L(0); PG8_BAR; PG8_MMA(1, 0, At, B0); PG8_MMA(1, 1, At, B1); PG8_BAR; PG8_SCHED;
.LBB0_849:
	s_add_i32 s76, 0, 0x10000
	v_add_u32_e32 v138, s76, v141
	s_add_i32 s78, 0, 0x14000
	ds_read_b128 v[144:147], v138
	ds_read_b128 v[148:151], v138 offset:1024
	ds_read_b128 v[152:155], v138 offset:2048
	ds_read_b128 v[156:159], v138 offset:3072
	v_add_u32_e32 v138, s78, v141
	ds_read_b128 v[164:167], v138
	ds_read_b128 v[168:171], v138 offset:1024
	ds_read_b128 v[172:175], v138 offset:2048
	ds_read_b128 v[176:179], v138 offset:3072
	s_add_i32 m0, s51, 0xc000
	ds_read_b128 v[180:183], v143
	ds_read_b128 v[184:187], v143 offset:1024
	ds_read_b128 v[188:191], v143 offset:2048
	ds_read_b128 v[192:195], v143 offset:3072
	ds_read_b128 v[196:199], v143 offset:4096
	ds_read_b128 v[222:225], v143 offset:5120
	ds_read_b128 v[226:229], v143 offset:6144
	ds_read_b128 v[230:233], v143 offset:7168
	global_load_lds_dwordx4 v134, s[70:71]
	s_add_i32 m0, s51, 0xe000
	s_nop 0
	global_load_lds_dwordx4 v136, s[70:71]
	s_add_u32 s4, s70, 0xfff80080
	s_addc_u32 s5, s71, -1
	s_cmp_eq_u32 s75, 28
	s_cselect_b32 s53, s11, s5
	s_cselect_b32 s52, s63, s4
	s_cselect_b32 s5, s13, s74
	s_cselect_b32 s4, s72, s73
	s_waitcnt vmcnt(8)
	s_waitcnt lgkmcnt(0)
	s_barrier
	s_setprio 1
	s_waitcnt lgkmcnt(0)
	v_mfma_f32_16x16x32_bf16 v[124:127], v[144:147], v[180:183], v[124:127]
	v_mfma_f32_16x16x32_bf16 v[116:119], v[152:155], v[180:183], v[116:119]
	v_mfma_f32_16x16x32_bf16 v[108:111], v[144:147], v[188:191], v[108:111]
	v_mfma_f32_16x16x32_bf16 v[100:103], v[152:155], v[188:191], v[100:103]
	v_mfma_f32_16x16x32_bf16 v[92:95], v[144:147], v[196:199], v[92:95]
	v_mfma_f32_16x16x32_bf16 v[84:87], v[152:155], v[196:199], v[84:87]
	v_mfma_f32_16x16x32_bf16 v[76:79], v[144:147], v[226:229], v[76:79]
	v_mfma_f32_16x16x32_bf16 v[68:71], v[152:155], v[226:229], v[68:71]
	v_mfma_f32_16x16x32_bf16 v[124:127], v[148:151], v[184:187], v[124:127]
	v_mfma_f32_16x16x32_bf16 v[116:119], v[156:159], v[184:187], v[116:119]
	v_mfma_f32_16x16x32_bf16 v[108:111], v[148:151], v[192:195], v[108:111]
	v_mfma_f32_16x16x32_bf16 v[100:103], v[156:159], v[192:195], v[100:103]
	v_mfma_f32_16x16x32_bf16 v[92:95], v[148:151], v[222:225], v[92:95]
	v_mfma_f32_16x16x32_bf16 v[84:87], v[156:159], v[222:225], v[84:87]
	v_mfma_f32_16x16x32_bf16 v[76:79], v[148:151], v[230:233], v[76:79]
	v_mfma_f32_16x16x32_bf16 v[68:71], v[156:159], v[230:233], v[68:71]
	s_setprio 0
	s_setprio 1
	v_mfma_f32_16x16x32_bf16 v[120:123], v[164:167], v[180:183], v[120:123]
	v_mfma_f32_16x16x32_bf16 v[112:115], v[172:175], v[180:183], v[112:115]
	v_mfma_f32_16x16x32_bf16 v[104:107], v[164:167], v[188:191], v[104:107]
	v_mfma_f32_16x16x32_bf16 v[96:99], v[172:175], v[188:191], v[96:99]
	v_mfma_f32_16x16x32_bf16 v[88:91], v[164:167], v[196:199], v[88:91]
	v_mfma_f32_16x16x32_bf16 v[80:83], v[172:175], v[196:199], v[80:83]
	v_mfma_f32_16x16x32_bf16 v[72:75], v[164:167], v[226:229], v[72:75]
	v_mfma_f32_16x16x32_bf16 v[64:67], v[172:175], v[226:229], v[64:67]
	v_mfma_f32_16x16x32_bf16 v[120:123], v[168:171], v[184:187], v[120:123]
	v_mfma_f32_16x16x32_bf16 v[112:115], v[176:179], v[184:187], v[112:115]
	v_mfma_f32_16x16x32_bf16 v[104:107], v[168:171], v[192:195], v[104:107]
	v_mfma_f32_16x16x32_bf16 v[96:99], v[176:179], v[192:195], v[96:99]
	v_mfma_f32_16x16x32_bf16 v[88:91], v[168:171], v[222:225], v[88:91]
	v_mfma_f32_16x16x32_bf16 v[80:83], v[176:179], v[222:225], v[80:83]
	v_mfma_f32_16x16x32_bf16 v[72:75], v[168:171], v[230:233], v[72:75]
	v_mfma_f32_16x16x32_bf16 v[64:67], v[176:179], v[230:233], v[64:67]
	s_setprio 0
	s_barrier
	s_add_i32 s76, s76, s24
	s_mov_b32 m0, s76
	ds_read_b128 v[180:183], v143 offset:16384
	ds_read_b128 v[184:187], v143 offset:17408
	ds_read_b128 v[188:191], v143 offset:18432
	ds_read_b128 v[192:195], v143 offset:19456
	ds_read_b128 v[196:199], v143 offset:20480
	ds_read_b128 v[222:225], v143 offset:21504
	ds_read_b128 v[226:229], v143 offset:22528
	ds_read_b128 v[230:233], v143 offset:23552
	global_load_lds_dwordx4 v160, s[4:5]
	s_add_i32 m0, s76, 0x2000
	s_add_u32 s76, s4, 0x80000
	s_addc_u32 s77, s5, 0
	s_add_i32 s78, s78, s24
	global_load_lds_dwordx4 v128, s[4:5]
	s_mov_b32 m0, s78
	s_nop 0
	global_load_lds_dwordx4 v160, s[76:77]
	s_add_i32 m0, s78, 0x2000
	s_nop 0
	global_load_lds_dwordx4 v128, s[76:77]
	s_mov_b32 m0, s51
	s_nop 0
	global_load_lds_dwordx4 v132, s[52:53]
	s_mov_b32 m0, s55
	s_nop 0
	global_load_lds_dwordx4 v130, s[52:53]
	s_add_u32 s98, s52, 0x80
	s_addc_u32 s99, s53, 0
	s_waitcnt vmcnt(8)
	s_waitcnt lgkmcnt(0)
	s_barrier
	s_setprio 1
	s_waitcnt lgkmcnt(0)
	v_mfma_f32_16x16x32_bf16 v[60:63], v[144:147], v[180:183], v[60:63]
	v_mfma_f32_16x16x32_bf16 v[52:55], v[152:155], v[180:183], v[52:55]
	v_mfma_f32_16x16x32_bf16 v[44:47], v[144:147], v[188:191], v[44:47]
	v_mfma_f32_16x16x32_bf16 v[36:39], v[152:155], v[188:191], v[36:39]
	v_mfma_f32_16x16x32_bf16 v[28:31], v[144:147], v[196:199], v[28:31]
	v_mfma_f32_16x16x32_bf16 v[20:23], v[152:155], v[196:199], v[20:23]
	v_mfma_f32_16x16x32_bf16 v[12:15], v[144:147], v[226:229], v[12:15]
	v_mfma_f32_16x16x32_bf16 v[4:7], v[152:155], v[226:229], v[4:7]
	v_mfma_f32_16x16x32_bf16 v[60:63], v[148:151], v[184:187], v[60:63]
	v_mfma_f32_16x16x32_bf16 v[52:55], v[156:159], v[184:187], v[52:55]
	v_mfma_f32_16x16x32_bf16 v[44:47], v[148:151], v[192:195], v[44:47]
	v_mfma_f32_16x16x32_bf16 v[36:39], v[156:159], v[192:195], v[36:39]
	v_mfma_f32_16x16x32_bf16 v[28:31], v[148:151], v[222:225], v[28:31]
	v_mfma_f32_16x16x32_bf16 v[20:23], v[156:159], v[222:225], v[20:23]
	v_mfma_f32_16x16x32_bf16 v[12:15], v[148:151], v[230:233], v[12:15]
	v_mfma_f32_16x16x32_bf16 v[4:7], v[156:159], v[230:233], v[4:7]
	s_setprio 0
	s_setprio 1
	v_mfma_f32_16x16x32_bf16 v[56:59], v[164:167], v[180:183], v[56:59]
	v_mfma_f32_16x16x32_bf16 v[48:51], v[172:175], v[180:183], v[48:51]
	v_mfma_f32_16x16x32_bf16 v[40:43], v[164:167], v[188:191], v[40:43]
	v_mfma_f32_16x16x32_bf16 v[32:35], v[172:175], v[188:191], v[32:35]
	v_mfma_f32_16x16x32_bf16 v[24:27], v[164:167], v[196:199], v[24:27]
	v_mfma_f32_16x16x32_bf16 v[16:19], v[172:175], v[196:199], v[16:19]
	v_mfma_f32_16x16x32_bf16 v[8:11], v[164:167], v[226:229], v[8:11]
	v_mfma_f32_16x16x32_bf16 v[0:3], v[172:175], v[226:229], v[0:3]
	v_mfma_f32_16x16x32_bf16 v[56:59], v[168:171], v[184:187], v[56:59]
	v_mfma_f32_16x16x32_bf16 v[48:51], v[176:179], v[184:187], v[48:51]
	v_mfma_f32_16x16x32_bf16 v[40:43], v[168:171], v[192:195], v[40:43]
	v_mfma_f32_16x16x32_bf16 v[32:35], v[176:179], v[192:195], v[32:35]
	v_mfma_f32_16x16x32_bf16 v[24:27], v[168:171], v[222:225], v[24:27]
	v_mfma_f32_16x16x32_bf16 v[16:19], v[176:179], v[222:225], v[16:19]
	v_mfma_f32_16x16x32_bf16 v[8:11], v[168:171], v[230:233], v[8:11]
	v_mfma_f32_16x16x32_bf16 v[0:3], v[176:179], v[230:233], v[0:3]
	s_setprio 0
	s_barrier
; #define PG8_STAGE(bufoff, gbase, voff) do { _Pragma("unroll") for (int _i = 0; _i < 2; ++_i) \
;         __builtin_amdgcn_global_load_lds((const unsigned*)((const char*)(gbase) + (voff)[_i]), (PG8_LAS unsigned*)(lds + (bufoff) + ldsw + _i * 8192), 16, 0, 0); } while (0)
; #define PG8_LDA(dst, b, h) do { _Pragma("unroll") for (int m = 0; m < 4; ++m) _Pragma("unroll") for (int k = 0; k < 2; ++k) dst[m][k] = *(const PG8_LAS bf16x8*)(lds + PG8_SA(b, h) + aoff + m * 2048 + k * 1024); } while (0)
; #define PG8_LDB(dst, b, h) do { _Pragma("unroll") for (int n = 0; n < 2; ++n) _Pragma("unroll") for (int k = 0; k < 2; ++k) dst[n][k] = *(const PG8_LAS bf16x8*)(lds + PG8_SB(b, h) + boff + n * 2048 + k * 1024); } while (0)
; #define PG8_MMA(ai, bj, At, Bt) do { __builtin_amdgcn_s_setprio(1); _Pragma("unroll") for (int m = 0; m < 4; ++m) _Pragma("unroll") for (int n = 0; n < 2; ++n) _Pragma("unroll") for (int k = 0; k < 2; ++k) \
;         acc[ai][bj][m][n] = __builtin_amdgcn_mfma_f32_16x16x32_bf16(Bt[n][k], At[m][k], acc[ai][bj][m][n], 0, 0, 0); __builtin_amdgcn_s_setprio(0); } while (0)
; #define PG8_WAIT_V(n) asm volatile("s_waitcnt vmcnt(" #n ")" ::: "memory")
; #define PG8_WAIT_L(n) asm volatile("s_waitcnt lgkmcnt(" #n ")" ::: "memory")
; #define PG8_BAR __builtin_amdgcn_s_barrier()
; #define PG8_SCHED __builtin_amdgcn_sched_barrier(0)
; template <class Epi, class Sched, bool ALIGN_EPI = false, bool SP2 = false>
; __device__ __forceinline__ void gemm_phase(PG8_LAS unsigned char* lds, const Gemm g, const Sched& S, const Epi& E) {
;     ...
;             PG8_LDB(B0, 1, 0); PG8_LDB(B1, 1, 1); PG8_SCHED; PG8_LDA(At, 1, 0); PG8_STAGE(PG8_SA(0, 1), a2 + hstep, voffA);
;             PG8_WAIT_V(8); PG8_WAIT_L(0); PG8_BAR; PG8_MMA(0, 0, At, B0); PG8_MMA(0, 1, At, B1); PG8_BAR; PG8_SCHED;
;             PG8_LDA(At, 1, 1); PG8_STAGE(PG8_SB(1, 0), b3, voffB); PG8_STAGE(PG8_SB(1, 1), b3 + hstep, voffB); PG8_STAGE(PG8_SA(1, 0), a3, voffA);
;             PG8_WAIT_V(8); PG8_WAIT_L(0); PG8_BAR; PG8_MMA(1, 0, At, B0); PG8_MMA(1, 1, At, B1); PG8_BAR; PG8_SCHED;
	s_add_i32 s76, 0, 0x18000
	s_add_i32 s77, 0, 0x1c000
	v_add_u32_e32 v156, s76, v141
	v_add_u32_e32 v163, s77, v141
	ds_read_b128 v[144:147], v156
	ds_read_b128 v[148:151], v156 offset:1024
	ds_read_b128 v[152:155], v156 offset:2048
	ds_read_b128 v[156:159], v156 offset:3072
	ds_read_b128 v[164:167], v163
	ds_read_b128 v[168:171], v163 offset:1024
	ds_read_b128 v[172:175], v163 offset:2048
	ds_read_b128 v[176:179], v163 offset:3072
	s_add_u32 s52, s52, 0x80000
	s_addc_u32 s53, s53, 0
	s_mov_b32 m0, s56
	ds_read_b128 v[180:183], v143 offset:32768
	ds_read_b128 v[184:187], v143 offset:33792
	ds_read_b128 v[188:191], v143 offset:34816
	ds_read_b128 v[192:195], v143 offset:35840
	ds_read_b128 v[196:199], v143 offset:36864
	ds_read_b128 v[222:225], v143 offset:37888
	ds_read_b128 v[226:229], v143 offset:38912
	ds_read_b128 v[230:233], v143 offset:39936
	global_load_lds_dwordx4 v132, s[52:53]
	s_mov_b32 m0, s57
	s_nop 0
	global_load_lds_dwordx4 v130, s[52:53]
	s_waitcnt vmcnt(8)
	s_waitcnt lgkmcnt(0)
	s_barrier
	s_setprio 1
	s_waitcnt lgkmcnt(0)
	v_mfma_f32_16x16x32_bf16 v[124:127], v[144:147], v[180:183], v[124:127]
	v_mfma_f32_16x16x32_bf16 v[116:119], v[152:155], v[180:183], v[116:119]
	v_mfma_f32_16x16x32_bf16 v[108:111], v[144:147], v[188:191], v[108:111]
	v_mfma_f32_16x16x32_bf16 v[100:103], v[152:155], v[188:191], v[100:103]
	v_mfma_f32_16x16x32_bf16 v[92:95], v[144:147], v[196:199], v[92:95]
	v_mfma_f32_16x16x32_bf16 v[84:87], v[152:155], v[196:199], v[84:87]
	v_mfma_f32_16x16x32_bf16 v[76:79], v[144:147], v[226:229], v[76:79]
	v_mfma_f32_16x16x32_bf16 v[68:71], v[152:155], v[226:229], v[68:71]
	v_mfma_f32_16x16x32_bf16 v[124:127], v[148:151], v[184:187], v[124:127]
	v_mfma_f32_16x16x32_bf16 v[116:119], v[156:159], v[184:187], v[116:119]
	v_mfma_f32_16x16x32_bf16 v[108:111], v[148:151], v[192:195], v[108:111]
	v_mfma_f32_16x16x32_bf16 v[100:103], v[156:159], v[192:195], v[100:103]
	v_mfma_f32_16x16x32_bf16 v[92:95], v[148:151], v[222:225], v[92:95]
	v_mfma_f32_16x16x32_bf16 v[84:87], v[156:159], v[222:225], v[84:87]
	v_mfma_f32_16x16x32_bf16 v[76:79], v[148:151], v[230:233], v[76:79]
	v_mfma_f32_16x16x32_bf16 v[68:71], v[156:159], v[230:233], v[68:71]
	s_setprio 0
	s_setprio 1
	v_mfma_f32_16x16x32_bf16 v[120:123], v[164:167], v[180:183], v[120:123]
	v_mfma_f32_16x16x32_bf16 v[112:115], v[172:175], v[180:183], v[112:115]
	v_mfma_f32_16x16x32_bf16 v[104:107], v[164:167], v[188:191], v[104:107]
	v_mfma_f32_16x16x32_bf16 v[96:99], v[172:175], v[188:191], v[96:99]
	v_mfma_f32_16x16x32_bf16 v[88:91], v[164:167], v[196:199], v[88:91]
	v_mfma_f32_16x16x32_bf16 v[80:83], v[172:175], v[196:199], v[80:83]
	v_mfma_f32_16x16x32_bf16 v[72:75], v[164:167], v[226:229], v[72:75]
	v_mfma_f32_16x16x32_bf16 v[64:67], v[172:175], v[226:229], v[64:67]
	v_mfma_f32_16x16x32_bf16 v[120:123], v[168:171], v[184:187], v[120:123]
	v_mfma_f32_16x16x32_bf16 v[112:115], v[176:179], v[184:187], v[112:115]
	v_mfma_f32_16x16x32_bf16 v[104:107], v[168:171], v[192:195], v[104:107]
	v_mfma_f32_16x16x32_bf16 v[96:99], v[176:179], v[192:195], v[96:99]
	v_mfma_f32_16x16x32_bf16 v[88:91], v[168:171], v[222:225], v[88:91]
	v_mfma_f32_16x16x32_bf16 v[80:83], v[176:179], v[222:225], v[80:83]
	v_mfma_f32_16x16x32_bf16 v[72:75], v[168:171], v[230:233], v[72:75]
	v_mfma_f32_16x16x32_bf16 v[64:67], v[176:179], v[230:233], v[64:67]
	s_setprio 0
	s_barrier
	s_add_i32 s52, s76, s24
	s_mov_b32 m0, s52
	ds_read_b128 v[180:183], v143 offset:49152
	ds_read_b128 v[184:187], v143 offset:50176
	ds_read_b128 v[188:191], v143 offset:51200
	ds_read_b128 v[192:195], v143 offset:52224
	ds_read_b128 v[196:199], v143 offset:53248
	ds_read_b128 v[222:225], v143 offset:54272
	ds_read_b128 v[226:229], v143 offset:55296
	ds_read_b128 v[230:233], v143 offset:56320
	s_add_u32 s4, s4, 0x80
	s_addc_u32 s5, s5, 0
	global_load_lds_dwordx4 v160, s[4:5]
	s_add_i32 m0, s52, 0x2000
	s_add_i32 s52, s77, s24
	global_load_lds_dwordx4 v128, s[4:5]
	s_add_u32 s4, s4, 0x80000
	s_addc_u32 s5, s5, 0
	s_mov_b32 m0, s52
	s_nop 0
	global_load_lds_dwordx4 v160, s[4:5]
	s_add_i32 m0, s52, 0x2000
	s_nop 0
	global_load_lds_dwordx4 v128, s[4:5]
	s_mov_b32 m0, s58
	s_nop 0
	global_load_lds_dwordx4 v132, s[98:99]
	s_mov_b32 m0, s59
	s_nop 0
	global_load_lds_dwordx4 v130, s[98:99]
	s_waitcnt vmcnt(8)
	s_waitcnt lgkmcnt(0)
	s_barrier
	s_setprio 1
	s_waitcnt lgkmcnt(0)
	v_mfma_f32_16x16x32_bf16 v[60:63], v[144:147], v[180:183], v[60:63]
	v_mfma_f32_16x16x32_bf16 v[52:55], v[152:155], v[180:183], v[52:55]
	v_mfma_f32_16x16x32_bf16 v[44:47], v[144:147], v[188:191], v[44:47]
	v_mfma_f32_16x16x32_bf16 v[36:39], v[152:155], v[188:191], v[36:39]
	v_mfma_f32_16x16x32_bf16 v[28:31], v[144:147], v[196:199], v[28:31]
	v_mfma_f32_16x16x32_bf16 v[20:23], v[152:155], v[196:199], v[20:23]
	v_mfma_f32_16x16x32_bf16 v[12:15], v[144:147], v[226:229], v[12:15]
	v_mfma_f32_16x16x32_bf16 v[4:7], v[152:155], v[226:229], v[4:7]
	v_mfma_f32_16x16x32_bf16 v[60:63], v[148:151], v[184:187], v[60:63]
	v_mfma_f32_16x16x32_bf16 v[52:55], v[156:159], v[184:187], v[52:55]
	v_mfma_f32_16x16x32_bf16 v[44:47], v[148:151], v[192:195], v[44:47]
	v_mfma_f32_16x16x32_bf16 v[36:39], v[156:159], v[192:195], v[36:39]
	v_mfma_f32_16x16x32_bf16 v[28:31], v[148:151], v[222:225], v[28:31]
	v_mfma_f32_16x16x32_bf16 v[20:23], v[156:159], v[222:225], v[20:23]
	v_mfma_f32_16x16x32_bf16 v[12:15], v[148:151], v[230:233], v[12:15]
	v_mfma_f32_16x16x32_bf16 v[4:7], v[156:159], v[230:233], v[4:7]
	s_setprio 0
	s_setprio 1
	v_mfma_f32_16x16x32_bf16 v[56:59], v[164:167], v[180:183], v[56:59]
	v_mfma_f32_16x16x32_bf16 v[48:51], v[172:175], v[180:183], v[48:51]
	v_mfma_f32_16x16x32_bf16 v[40:43], v[164:167], v[188:191], v[40:43]
	v_mfma_f32_16x16x32_bf16 v[32:35], v[172:175], v[188:191], v[32:35]
	v_mfma_f32_16x16x32_bf16 v[24:27], v[164:167], v[196:199], v[24:27]
	v_mfma_f32_16x16x32_bf16 v[16:19], v[172:175], v[196:199], v[16:19]
	v_mfma_f32_16x16x32_bf16 v[8:11], v[164:167], v[226:229], v[8:11]
	v_mfma_f32_16x16x32_bf16 v[0:3], v[172:175], v[226:229], v[0:3]
	v_mfma_f32_16x16x32_bf16 v[56:59], v[168:171], v[184:187], v[56:59]
	v_mfma_f32_16x16x32_bf16 v[48:51], v[176:179], v[184:187], v[48:51]
	v_mfma_f32_16x16x32_bf16 v[40:43], v[168:171], v[192:195], v[40:43]
	v_mfma_f32_16x16x32_bf16 v[32:35], v[176:179], v[192:195], v[32:35]
	v_mfma_f32_16x16x32_bf16 v[24:27], v[168:171], v[222:225], v[24:27]
	v_mfma_f32_16x16x32_bf16 v[16:19], v[176:179], v[222:225], v[16:19]
	v_mfma_f32_16x16x32_bf16 v[8:11], v[168:171], v[230:233], v[8:11]
	v_mfma_f32_16x16x32_bf16 v[0:3], v[176:179], v[230:233], v[0:3]
	s_setprio 0
	s_barrier
	s_add_i32 s75, s75, 2
	s_add_u32 s70, s70, 0x100
	s_addc_u32 s71, s71, 0
	s_add_u32 s73, s73, 0x100
	s_addc_u32 s74, s74, 0
	s_cmp_gt_u32 s75, 29
	s_cbranch_scc0 .LBB0_849
	s_and_b64 vcc, exec, s[8:9]
	s_cbranch_vccz .LBB0_852
	s_barrier
